# conversion blocks of the co-scheduled attention phases: 64 scalar scale multiplies per item -> 32 in-place v_pk_mul_f32 (same products), packs read the scaled registers
# speedup vs baseline: 1.0012x; 1.0012x over previous
.Lp5_i2_1168:
	s_lshl_b64 s[44:45], s[44:45], 2
	s_waitcnt lgkmcnt(0)
	s_add_u32 s20, s42, s44
	s_addc_u32 s43, s43, s45
	s_bfe_u32 s44, s53, 0x70003
	s_lshl_b32 s42, s44, 17
	s_add_u32 s42, s20, s42
	s_addc_u32 s43, s43, 0
	v_lshlrev_b32_e32 v224, 2, v224
	v_lshl_add_u64 v[232:233], s[42:43], 0, v[224:225]
	global_load_dwordx4 v[148:151], v224, s[42:43] nt
	s_nop 0
	v_mov_b32_e32 v212, v23
	v_mov_b32_e32 v213, v23
	v_mov_b32_e32 v214, v23
	v_mov_b32_e32 v215, v23
	v_mov_b32_e32 v216, v23
	v_mov_b32_e32 v217, v23
	v_mov_b32_e32 v218, v23
	v_mov_b32_e32 v219, v23
	v_mov_b32_e32 v220, v23
	v_mov_b32_e32 v221, v23
	v_mov_b32_e32 v222, v23
	v_mov_b32_e32 v223, v23
	s_mul_i32 s20, s40, s44
	v_ashrrev_i32_e32 v229, 31, v228
	v_lshl_add_u64 v[228:229], s[20:21], 0, v[228:229]
	v_lshl_add_u64 v[228:229], v[228:229], 4, s[38:39]
	s_mov_b32 s100, s41
	s_addk_i32 s53, 0x400
	s_waitcnt vmcnt(21)
	v_add_co_u32_e32 v152, vcc, s64, v232
	v_addc_co_u32_e32 v153, vcc, 0, v233, vcc
	global_load_dwordx4 v[152:155], v[152:153], off nt
	s_nop 0
	v_pk_mul_f32 v[72:73], v[72:73], s[98:99] op_sel_hi:[1,0]
	s_waitcnt vmcnt(21)
	v_add_co_u32_e32 v156, vcc, s65, v232
	v_addc_co_u32_e32 v157, vcc, 0, v233, vcc
	global_load_dwordx4 v[156:159], v[156:157], off nt
	s_nop 0
	v_pk_mul_f32 v[76:77], v[76:77], s[98:99] op_sel_hi:[1,0]
	v_cvt_pk_fp8_f32 v136, v72, v76
	s_waitcnt vmcnt(21)
	v_add_co_u32_e32 v160, vcc, s66, v232
	v_addc_co_u32_e32 v161, vcc, 0, v233, vcc
	global_load_dwordx4 v[160:163], v[160:161], off nt
	s_nop 0
	v_pk_mul_f32 v[80:81], v[80:81], s[98:99] op_sel_hi:[1,0]
	s_waitcnt vmcnt(21)
	v_add_co_u32_e32 v164, vcc, s67, v232
	v_addc_co_u32_e32 v165, vcc, 0, v233, vcc
	global_load_dwordx4 v[164:167], v[164:165], off nt
	s_nop 0
	v_pk_mul_f32 v[84:85], v[84:85], s[98:99] op_sel_hi:[1,0]
	s_waitcnt vmcnt(21)
	v_add_co_u32_e32 v168, vcc, s68, v232
	v_addc_co_u32_e32 v169, vcc, 0, v233, vcc
	global_load_dwordx4 v[168:171], v[168:169], off nt
	s_nop 0
	v_pk_mul_f32 v[88:89], v[88:89], s[98:99] op_sel_hi:[1,0]
	v_cvt_pk_fp8_f32 v136, v80, v84 op_sel:[0,0,1]
	s_waitcnt vmcnt(21)
	v_add_co_u32_e32 v172, vcc, s69, v232
	v_addc_co_u32_e32 v173, vcc, 0, v233, vcc
	global_load_dwordx4 v[172:175], v[172:173], off nt
	s_nop 0
	v_pk_mul_f32 v[92:93], v[92:93], s[98:99] op_sel_hi:[1,0]
	v_cvt_pk_fp8_f32 v137, v88, v92
	s_waitcnt vmcnt(21)
	v_add_co_u32_e32 v176, vcc, s70, v232
	v_addc_co_u32_e32 v177, vcc, 0, v233, vcc
	global_load_dwordx4 v[176:179], v[176:177], off nt
	s_nop 0
	v_pk_mul_f32 v[96:97], v[96:97], s[98:99] op_sel_hi:[1,0]
	s_waitcnt vmcnt(21)
	v_add_co_u32_e32 v180, vcc, s71, v232
	v_addc_co_u32_e32 v181, vcc, 0, v233, vcc
	global_load_dwordx4 v[180:183], v[180:181], off nt
	s_nop 0
	v_pk_mul_f32 v[100:101], v[100:101], s[98:99] op_sel_hi:[1,0]
	v_cvt_pk_fp8_f32 v137, v96, v100 op_sel:[0,0,1]
	s_waitcnt vmcnt(21)
	v_add_co_u32_e32 v184, vcc, s72, v232
	v_addc_co_u32_e32 v185, vcc, 0, v233, vcc
	global_load_dwordx4 v[184:187], v[184:185], off nt
	s_nop 0
	v_pk_mul_f32 v[104:105], v[104:105], s[98:99] op_sel_hi:[1,0]
	s_waitcnt vmcnt(21)
	v_add_co_u32_e32 v188, vcc, s73, v232
	v_addc_co_u32_e32 v189, vcc, 0, v233, vcc
	global_load_dwordx4 v[188:191], v[188:189], off nt
	s_nop 0
	v_pk_mul_f32 v[108:109], v[108:109], s[98:99] op_sel_hi:[1,0]
	v_cvt_pk_fp8_f32 v138, v104, v108
	s_waitcnt vmcnt(21)
	v_add_co_u32_e32 v192, vcc, s74, v232
	v_addc_co_u32_e32 v193, vcc, 0, v233, vcc
	global_load_dwordx4 v[192:195], v[192:193], off nt
	s_nop 0
	v_pk_mul_f32 v[112:113], v[112:113], s[98:99] op_sel_hi:[1,0]
	s_waitcnt vmcnt(21)
	v_add_co_u32_e32 v196, vcc, s75, v232
	v_addc_co_u32_e32 v197, vcc, 0, v233, vcc
	global_load_dwordx4 v[196:199], v[196:197], off nt
	s_nop 0
	v_pk_mul_f32 v[116:117], v[116:117], s[98:99] op_sel_hi:[1,0]
	s_waitcnt vmcnt(21)
	v_add_co_u32_e32 v200, vcc, s76, v232
	v_addc_co_u32_e32 v201, vcc, 0, v233, vcc
	global_load_dwordx4 v[200:203], v[200:201], off nt
	s_nop 0
	v_pk_mul_f32 v[120:121], v[120:121], s[98:99] op_sel_hi:[1,0]
	v_cvt_pk_fp8_f32 v138, v112, v116 op_sel:[0,0,1]
	s_waitcnt vmcnt(21)
	v_add_co_u32_e32 v204, vcc, s77, v232
	v_addc_co_u32_e32 v205, vcc, 0, v233, vcc
	global_load_dwordx4 v[204:207], v[204:205], off nt
	s_nop 0
	v_pk_mul_f32 v[124:125], v[124:125], s[98:99] op_sel_hi:[1,0]
	v_cvt_pk_fp8_f32 v139, v120, v124
	s_waitcnt vmcnt(21)
	v_add_co_u32_e32 v208, vcc, s78, v232
	v_addc_co_u32_e32 v209, vcc, 0, v233, vcc
	global_load_dwordx4 v[208:211], v[208:209], off nt
	s_nop 0
	v_pk_mul_f32 v[128:129], v[128:129], s[98:99] op_sel_hi:[1,0]
	s_waitcnt vmcnt(21)
	v_pk_mul_f32 v[132:133], v[132:133], s[98:99] op_sel_hi:[1,0]
	v_cvt_pk_fp8_f32 v139, v128, v132 op_sel:[0,0,1]
	v_cvt_pk_fp8_f32 v140, v73, v77
	v_cvt_pk_fp8_f32 v141, v89, v93
	v_cvt_pk_fp8_f32 v141, v97, v101 op_sel:[0,0,1]
	v_cvt_pk_fp8_f32 v142, v105, v109
	v_cvt_pk_fp8_f32 v143, v121, v125
	v_cvt_pk_fp8_f32 v140, v81, v85 op_sel:[0,0,1]
	v_cvt_pk_fp8_f32 v143, v129, v133 op_sel:[0,0,1]
	v_pk_mul_f32 v[74:75], v[74:75], s[98:99] op_sel_hi:[1,0]
	v_pk_mul_f32 v[78:79], v[78:79], s[98:99] op_sel_hi:[1,0]
	v_cvt_pk_fp8_f32 v144, v74, v78
	v_pk_mul_f32 v[90:91], v[90:91], s[98:99] op_sel_hi:[1,0]
	v_pk_mul_f32 v[94:95], v[94:95], s[98:99] op_sel_hi:[1,0]
	v_cvt_pk_fp8_f32 v145, v90, v94
	v_pk_mul_f32 v[98:99], v[98:99], s[98:99] op_sel_hi:[1,0]
	v_pk_mul_f32 v[102:103], v[102:103], s[98:99] op_sel_hi:[1,0]
	v_cvt_pk_fp8_f32 v145, v98, v102 op_sel:[0,0,1]
	v_pk_mul_f32 v[106:107], v[106:107], s[98:99] op_sel_hi:[1,0]
	v_pk_mul_f32 v[110:111], v[110:111], s[98:99] op_sel_hi:[1,0]
	v_cvt_pk_fp8_f32 v146, v106, v110
	v_pk_mul_f32 v[122:123], v[122:123], s[98:99] op_sel_hi:[1,0]
	v_pk_mul_f32 v[126:127], v[126:127], s[98:99] op_sel_hi:[1,0]
	v_cvt_pk_fp8_f32 v147, v122, v126
	v_cvt_pk_fp8_f32 v142, v113, v117 op_sel:[0,0,1]
	v_pk_mul_f32 v[82:83], v[82:83], s[98:99] op_sel_hi:[1,0]
	v_pk_mul_f32 v[86:87], v[86:87], s[98:99] op_sel_hi:[1,0]
	v_cvt_pk_fp8_f32 v144, v82, v86 op_sel:[0,0,1]
	v_pk_mul_f32 v[114:115], v[114:115], s[98:99] op_sel_hi:[1,0]
	v_pk_mul_f32 v[118:119], v[118:119], s[98:99] op_sel_hi:[1,0]
	v_pk_mul_f32 v[130:131], v[130:131], s[98:99] op_sel_hi:[1,0]
	v_pk_mul_f32 v[134:135], v[134:135], s[98:99] op_sel_hi:[1,0]
	v_cvt_pk_fp8_f32 v146, v114, v118 op_sel:[0,0,1]
	v_cvt_pk_fp8_f32 v147, v130, v134 op_sel:[0,0,1]
	v_mov_b32_e32 v72, v23
	v_cvt_pk_fp8_f32 v72, v75, v79
	v_mov_b32_e32 v73, v23
	v_cvt_pk_fp8_f32 v73, v91, v95
	v_cvt_pk_fp8_f32 v72, v83, v87 op_sel:[0,0,1]
	v_cvt_pk_fp8_f32 v73, v99, v103 op_sel:[0,0,1]
	v_mov_b32_e32 v74, v23
	v_cvt_pk_fp8_f32 v74, v107, v111
	v_mov_b32_e32 v75, v23
	v_cvt_pk_fp8_f32 v75, v123, v127
	v_cvt_pk_fp8_f32 v74, v115, v119 op_sel:[0,0,1]
	v_cvt_pk_fp8_f32 v75, v131, v135 op_sel:[0,0,1]
	global_store_dwordx4 v[226:227], v[136:139], off
	global_store_dwordx4 v[226:227], v[140:143], off offset:16
	global_store_dwordx4 v[226:227], v[144:147], off offset:32
	global_store_dwordx4 v[226:227], v[72:75], off offset:48
	s_mov_b32 s99, 4
	s_waitcnt vmcnt(20)
	s_andn2_b32 s20, 1, s84
	s_mul_i32 s20, s20, 0xa800
	s_add_i32 s20, s20, 0
	v_add3_u32 v22, s20, v61, v62
	ds_write_b128 v22, v[0:3]
	v_add3_u32 v22, s20, v63, v64
	ds_write_b128 v22, v[4:7]
	v_add3_u32 v22, s20, v65, v66
	ds_write_b128 v22, v[8:11]
	v_add_u32_e32 v22, s20, v20
	v_add3_u32 v48, v22, v67, s63
	v_add3_u32 v22, v22, v68, s63
	ds_write2_b64 v48, v[12:13], v[14:15] offset1:1
	ds_write2_b64 v22, v[16:17], v[18:19] offset1:1
	s_branch .LBB0_1160
.Lp5_st1c:
	s_waitcnt vmcnt(20)
	v_pk_mul_f32 v[72:73], v[72:73], s[98:99] op_sel_hi:[1,0]
	s_waitcnt vmcnt(19)
	v_pk_mul_f32 v[76:77], v[76:77], s[98:99] op_sel_hi:[1,0]
	v_cvt_pk_fp8_f32 v136, v72, v76
	s_waitcnt vmcnt(18)
	v_pk_mul_f32 v[80:81], v[80:81], s[98:99] op_sel_hi:[1,0]
	s_waitcnt vmcnt(17)
	v_pk_mul_f32 v[84:85], v[84:85], s[98:99] op_sel_hi:[1,0]
	s_waitcnt vmcnt(16)
	v_pk_mul_f32 v[88:89], v[88:89], s[98:99] op_sel_hi:[1,0]
	v_cvt_pk_fp8_f32 v136, v80, v84 op_sel:[0,0,1]
	s_waitcnt vmcnt(15)
	v_pk_mul_f32 v[92:93], v[92:93], s[98:99] op_sel_hi:[1,0]
	v_cvt_pk_fp8_f32 v137, v88, v92
	s_waitcnt vmcnt(14)
	v_pk_mul_f32 v[96:97], v[96:97], s[98:99] op_sel_hi:[1,0]
	s_waitcnt vmcnt(13)
	v_pk_mul_f32 v[100:101], v[100:101], s[98:99] op_sel_hi:[1,0]
	v_cvt_pk_fp8_f32 v137, v96, v100 op_sel:[0,0,1]
	s_waitcnt vmcnt(12)
	v_pk_mul_f32 v[104:105], v[104:105], s[98:99] op_sel_hi:[1,0]
	s_waitcnt vmcnt(11)
	v_pk_mul_f32 v[108:109], v[108:109], s[98:99] op_sel_hi:[1,0]
	v_cvt_pk_fp8_f32 v138, v104, v108
	s_waitcnt vmcnt(10)
	v_pk_mul_f32 v[112:113], v[112:113], s[98:99] op_sel_hi:[1,0]
	s_waitcnt vmcnt(9)
	v_pk_mul_f32 v[116:117], v[116:117], s[98:99] op_sel_hi:[1,0]
	s_waitcnt vmcnt(8)
	v_pk_mul_f32 v[120:121], v[120:121], s[98:99] op_sel_hi:[1,0]
	v_cvt_pk_fp8_f32 v138, v112, v116 op_sel:[0,0,1]
	s_waitcnt vmcnt(7)
	v_pk_mul_f32 v[124:125], v[124:125], s[98:99] op_sel_hi:[1,0]
	v_cvt_pk_fp8_f32 v139, v120, v124
	s_waitcnt vmcnt(6)
	v_pk_mul_f32 v[128:129], v[128:129], s[98:99] op_sel_hi:[1,0]
	s_waitcnt vmcnt(5)
	v_pk_mul_f32 v[132:133], v[132:133], s[98:99] op_sel_hi:[1,0]
	v_cvt_pk_fp8_f32 v139, v128, v132 op_sel:[0,0,1]
	v_cvt_pk_fp8_f32 v140, v73, v77
	v_cvt_pk_fp8_f32 v141, v89, v93
	v_cvt_pk_fp8_f32 v141, v97, v101 op_sel:[0,0,1]
	v_cvt_pk_fp8_f32 v142, v105, v109
	v_cvt_pk_fp8_f32 v143, v121, v125
	v_cvt_pk_fp8_f32 v140, v81, v85 op_sel:[0,0,1]
	v_cvt_pk_fp8_f32 v143, v129, v133 op_sel:[0,0,1]
	v_pk_mul_f32 v[74:75], v[74:75], s[98:99] op_sel_hi:[1,0]
	v_pk_mul_f32 v[78:79], v[78:79], s[98:99] op_sel_hi:[1,0]
	v_cvt_pk_fp8_f32 v144, v74, v78
	v_pk_mul_f32 v[90:91], v[90:91], s[98:99] op_sel_hi:[1,0]
	v_pk_mul_f32 v[94:95], v[94:95], s[98:99] op_sel_hi:[1,0]
	v_cvt_pk_fp8_f32 v145, v90, v94
	v_pk_mul_f32 v[98:99], v[98:99], s[98:99] op_sel_hi:[1,0]
	v_pk_mul_f32 v[102:103], v[102:103], s[98:99] op_sel_hi:[1,0]
	v_cvt_pk_fp8_f32 v145, v98, v102 op_sel:[0,0,1]
	v_pk_mul_f32 v[106:107], v[106:107], s[98:99] op_sel_hi:[1,0]
	v_pk_mul_f32 v[110:111], v[110:111], s[98:99] op_sel_hi:[1,0]
	v_cvt_pk_fp8_f32 v146, v106, v110
	v_pk_mul_f32 v[122:123], v[122:123], s[98:99] op_sel_hi:[1,0]
	v_pk_mul_f32 v[126:127], v[126:127], s[98:99] op_sel_hi:[1,0]
	v_cvt_pk_fp8_f32 v147, v122, v126
	v_cvt_pk_fp8_f32 v142, v113, v117 op_sel:[0,0,1]
	v_pk_mul_f32 v[82:83], v[82:83], s[98:99] op_sel_hi:[1,0]
	v_pk_mul_f32 v[86:87], v[86:87], s[98:99] op_sel_hi:[1,0]
	v_cvt_pk_fp8_f32 v144, v82, v86 op_sel:[0,0,1]
	v_pk_mul_f32 v[114:115], v[114:115], s[98:99] op_sel_hi:[1,0]
	v_pk_mul_f32 v[118:119], v[118:119], s[98:99] op_sel_hi:[1,0]
	v_pk_mul_f32 v[130:131], v[130:131], s[98:99] op_sel_hi:[1,0]
	v_pk_mul_f32 v[134:135], v[134:135], s[98:99] op_sel_hi:[1,0]
	v_cvt_pk_fp8_f32 v146, v114, v118 op_sel:[0,0,1]
	v_cvt_pk_fp8_f32 v147, v130, v134 op_sel:[0,0,1]
	v_mov_b32_e32 v72, v23
	v_cvt_pk_fp8_f32 v72, v75, v79
	v_mov_b32_e32 v73, v23
	v_cvt_pk_fp8_f32 v73, v91, v95
	v_cvt_pk_fp8_f32 v72, v83, v87 op_sel:[0,0,1]
	v_cvt_pk_fp8_f32 v73, v99, v103 op_sel:[0,0,1]
	v_mov_b32_e32 v74, v23
	v_cvt_pk_fp8_f32 v74, v107, v111
	v_mov_b32_e32 v75, v23
	v_cvt_pk_fp8_f32 v75, v123, v127
	v_cvt_pk_fp8_f32 v74, v115, v119 op_sel:[0,0,1]
	v_cvt_pk_fp8_f32 v75, v131, v135 op_sel:[0,0,1]
	global_store_dwordx4 v[226:227], v[136:139], off
	global_store_dwordx4 v[226:227], v[140:143], off offset:16
	global_store_dwordx4 v[226:227], v[144:147], off offset:32
	global_store_dwordx4 v[226:227], v[72:75], off offset:48
	s_mov_b32 s99, 0
	s_waitcnt vmcnt(4)
	s_andn2_b32 s20, 1, s84
	s_mul_i32 s20, s20, 0xa800
	s_add_i32 s20, s20, 0
	v_add3_u32 v22, s20, v61, v62
	ds_write_b128 v22, v[0:3]
	v_add3_u32 v22, s20, v63, v64
	ds_write_b128 v22, v[4:7]
	v_add3_u32 v22, s20, v65, v66
	ds_write_b128 v22, v[8:11]
	v_add_u32_e32 v22, s20, v20
	v_add3_u32 v48, v22, v67, s63
	v_add3_u32 v22, v22, v68, s63
	ds_write2_b64 v48, v[12:13], v[14:15] offset1:1
	ds_write2_b64 v22, v[16:17], v[18:19] offset1:1
	s_branch .LBB0_1160

.Lp5_i3_1168:
	s_lshl_b64 s[44:45], s[44:45], 2
	s_waitcnt lgkmcnt(0)
	s_add_u32 s20, s42, s44
	s_addc_u32 s43, s43, s45
	s_bfe_u32 s44, s53, 0x70003
	s_lshl_b32 s42, s44, 17
	s_add_u32 s42, s20, s42
	s_addc_u32 s43, s43, 0
	v_lshlrev_b32_e32 v224, 2, v224
	v_lshl_add_u64 v[232:233], s[42:43], 0, v[224:225]
	global_load_dwordx4 v[148:151], v224, s[42:43] nt
	s_nop 0
	v_mov_b32_e32 v212, v23
	v_mov_b32_e32 v213, v23
	v_mov_b32_e32 v214, v23
	v_mov_b32_e32 v215, v23
	v_mov_b32_e32 v216, v23
	v_mov_b32_e32 v217, v23
	v_mov_b32_e32 v218, v23
	v_mov_b32_e32 v219, v23
	v_mov_b32_e32 v220, v23
	v_mov_b32_e32 v221, v23
	v_mov_b32_e32 v222, v23
	v_mov_b32_e32 v223, v23
	s_mul_i32 s20, s40, s44
	v_ashrrev_i32_e32 v229, 31, v228
	v_lshl_add_u64 v[228:229], s[20:21], 0, v[228:229]
	v_lshl_add_u64 v[228:229], v[228:229], 4, s[38:39]
	s_mov_b32 s100, s41
	s_addk_i32 s53, 0x400
	s_waitcnt vmcnt(25)
	v_add_co_u32_e32 v152, vcc, s64, v232
	v_addc_co_u32_e32 v153, vcc, 0, v233, vcc
	global_load_dwordx4 v[152:155], v[152:153], off nt
	s_nop 0
	v_pk_mul_f32 v[72:73], v[72:73], s[98:99] op_sel_hi:[1,0]
	s_waitcnt vmcnt(25)
	v_add_co_u32_e32 v156, vcc, s65, v232
	v_addc_co_u32_e32 v157, vcc, 0, v233, vcc
	global_load_dwordx4 v[156:159], v[156:157], off nt
	s_nop 0
	v_pk_mul_f32 v[76:77], v[76:77], s[98:99] op_sel_hi:[1,0]
	v_cvt_pk_fp8_f32 v136, v72, v76
	s_waitcnt vmcnt(25)
	v_add_co_u32_e32 v160, vcc, s66, v232
	v_addc_co_u32_e32 v161, vcc, 0, v233, vcc
	global_load_dwordx4 v[160:163], v[160:161], off nt
	s_nop 0
	v_pk_mul_f32 v[80:81], v[80:81], s[98:99] op_sel_hi:[1,0]
	s_waitcnt vmcnt(25)
	v_add_co_u32_e32 v164, vcc, s67, v232
	v_addc_co_u32_e32 v165, vcc, 0, v233, vcc
	global_load_dwordx4 v[164:167], v[164:165], off nt
	s_nop 0
	v_pk_mul_f32 v[84:85], v[84:85], s[98:99] op_sel_hi:[1,0]
	s_waitcnt vmcnt(25)
	v_add_co_u32_e32 v168, vcc, s68, v232
	v_addc_co_u32_e32 v169, vcc, 0, v233, vcc
	global_load_dwordx4 v[168:171], v[168:169], off nt
	s_nop 0
	v_pk_mul_f32 v[88:89], v[88:89], s[98:99] op_sel_hi:[1,0]
	v_cvt_pk_fp8_f32 v136, v80, v84 op_sel:[0,0,1]
	s_waitcnt vmcnt(25)
	v_add_co_u32_e32 v172, vcc, s69, v232
	v_addc_co_u32_e32 v173, vcc, 0, v233, vcc
	global_load_dwordx4 v[172:175], v[172:173], off nt
	s_nop 0
	v_pk_mul_f32 v[92:93], v[92:93], s[98:99] op_sel_hi:[1,0]
	v_cvt_pk_fp8_f32 v137, v88, v92
	s_waitcnt vmcnt(25)
	v_add_co_u32_e32 v176, vcc, s70, v232
	v_addc_co_u32_e32 v177, vcc, 0, v233, vcc
	global_load_dwordx4 v[176:179], v[176:177], off nt
	s_nop 0
	v_pk_mul_f32 v[96:97], v[96:97], s[98:99] op_sel_hi:[1,0]
	s_waitcnt vmcnt(25)
	v_add_co_u32_e32 v180, vcc, s71, v232
	v_addc_co_u32_e32 v181, vcc, 0, v233, vcc
	global_load_dwordx4 v[180:183], v[180:181], off nt
	s_nop 0
	v_pk_mul_f32 v[100:101], v[100:101], s[98:99] op_sel_hi:[1,0]
	v_cvt_pk_fp8_f32 v137, v96, v100 op_sel:[0,0,1]
	s_waitcnt vmcnt(25)
	v_add_co_u32_e32 v184, vcc, s72, v232
	v_addc_co_u32_e32 v185, vcc, 0, v233, vcc
	global_load_dwordx4 v[184:187], v[184:185], off nt
	s_nop 0
	v_pk_mul_f32 v[104:105], v[104:105], s[98:99] op_sel_hi:[1,0]
	s_waitcnt vmcnt(25)
	v_add_co_u32_e32 v188, vcc, s73, v232
	v_addc_co_u32_e32 v189, vcc, 0, v233, vcc
	global_load_dwordx4 v[188:191], v[188:189], off nt
	s_nop 0
	v_pk_mul_f32 v[108:109], v[108:109], s[98:99] op_sel_hi:[1,0]
	v_cvt_pk_fp8_f32 v138, v104, v108
	s_waitcnt vmcnt(25)
	v_add_co_u32_e32 v192, vcc, s74, v232
	v_addc_co_u32_e32 v193, vcc, 0, v233, vcc
	global_load_dwordx4 v[192:195], v[192:193], off nt
	s_nop 0
	v_pk_mul_f32 v[112:113], v[112:113], s[98:99] op_sel_hi:[1,0]
	s_waitcnt vmcnt(25)
	v_add_co_u32_e32 v196, vcc, s75, v232
	v_addc_co_u32_e32 v197, vcc, 0, v233, vcc
	global_load_dwordx4 v[196:199], v[196:197], off nt
	s_nop 0
	v_pk_mul_f32 v[116:117], v[116:117], s[98:99] op_sel_hi:[1,0]
	s_waitcnt vmcnt(25)
	v_add_co_u32_e32 v200, vcc, s76, v232
	v_addc_co_u32_e32 v201, vcc, 0, v233, vcc
	global_load_dwordx4 v[200:203], v[200:201], off nt
	s_nop 0
	v_pk_mul_f32 v[120:121], v[120:121], s[98:99] op_sel_hi:[1,0]
	v_cvt_pk_fp8_f32 v138, v112, v116 op_sel:[0,0,1]
	s_waitcnt vmcnt(25)
	v_add_co_u32_e32 v204, vcc, s77, v232
	v_addc_co_u32_e32 v205, vcc, 0, v233, vcc
	global_load_dwordx4 v[204:207], v[204:205], off nt
	s_nop 0
	v_pk_mul_f32 v[124:125], v[124:125], s[98:99] op_sel_hi:[1,0]
	v_cvt_pk_fp8_f32 v139, v120, v124
	s_waitcnt vmcnt(25)
	v_add_co_u32_e32 v208, vcc, s78, v232
	v_addc_co_u32_e32 v209, vcc, 0, v233, vcc
	global_load_dwordx4 v[208:211], v[208:209], off nt
	s_nop 0
	v_pk_mul_f32 v[128:129], v[128:129], s[98:99] op_sel_hi:[1,0]
	s_waitcnt vmcnt(25)
	v_pk_mul_f32 v[132:133], v[132:133], s[98:99] op_sel_hi:[1,0]
	v_cvt_pk_fp8_f32 v139, v128, v132 op_sel:[0,0,1]
	v_cvt_pk_fp8_f32 v140, v73, v77
	v_cvt_pk_fp8_f32 v141, v89, v93
	v_cvt_pk_fp8_f32 v141, v97, v101 op_sel:[0,0,1]
	v_cvt_pk_fp8_f32 v142, v105, v109
	v_cvt_pk_fp8_f32 v143, v121, v125
	v_cvt_pk_fp8_f32 v140, v81, v85 op_sel:[0,0,1]
	v_cvt_pk_fp8_f32 v143, v129, v133 op_sel:[0,0,1]
	v_pk_mul_f32 v[74:75], v[74:75], s[98:99] op_sel_hi:[1,0]
	v_pk_mul_f32 v[78:79], v[78:79], s[98:99] op_sel_hi:[1,0]
	v_cvt_pk_fp8_f32 v144, v74, v78
	v_pk_mul_f32 v[90:91], v[90:91], s[98:99] op_sel_hi:[1,0]
	v_pk_mul_f32 v[94:95], v[94:95], s[98:99] op_sel_hi:[1,0]
	v_cvt_pk_fp8_f32 v145, v90, v94
	v_pk_mul_f32 v[98:99], v[98:99], s[98:99] op_sel_hi:[1,0]
	v_pk_mul_f32 v[102:103], v[102:103], s[98:99] op_sel_hi:[1,0]
	v_cvt_pk_fp8_f32 v145, v98, v102 op_sel:[0,0,1]
	v_pk_mul_f32 v[106:107], v[106:107], s[98:99] op_sel_hi:[1,0]
	v_pk_mul_f32 v[110:111], v[110:111], s[98:99] op_sel_hi:[1,0]
	v_cvt_pk_fp8_f32 v146, v106, v110
	v_pk_mul_f32 v[122:123], v[122:123], s[98:99] op_sel_hi:[1,0]
	v_pk_mul_f32 v[126:127], v[126:127], s[98:99] op_sel_hi:[1,0]
	v_cvt_pk_fp8_f32 v147, v122, v126
	v_cvt_pk_fp8_f32 v142, v113, v117 op_sel:[0,0,1]
	v_pk_mul_f32 v[82:83], v[82:83], s[98:99] op_sel_hi:[1,0]
	v_pk_mul_f32 v[86:87], v[86:87], s[98:99] op_sel_hi:[1,0]
	v_cvt_pk_fp8_f32 v144, v82, v86 op_sel:[0,0,1]
	v_pk_mul_f32 v[114:115], v[114:115], s[98:99] op_sel_hi:[1,0]
	v_pk_mul_f32 v[118:119], v[118:119], s[98:99] op_sel_hi:[1,0]
	v_pk_mul_f32 v[130:131], v[130:131], s[98:99] op_sel_hi:[1,0]
	v_pk_mul_f32 v[134:135], v[134:135], s[98:99] op_sel_hi:[1,0]
	v_cvt_pk_fp8_f32 v146, v114, v118 op_sel:[0,0,1]
	v_cvt_pk_fp8_f32 v147, v130, v134 op_sel:[0,0,1]
	v_mov_b32_e32 v72, v23
	v_cvt_pk_fp8_f32 v72, v75, v79
	v_mov_b32_e32 v73, v23
	v_cvt_pk_fp8_f32 v73, v91, v95
	v_cvt_pk_fp8_f32 v72, v83, v87 op_sel:[0,0,1]
	v_cvt_pk_fp8_f32 v73, v99, v103 op_sel:[0,0,1]
	v_mov_b32_e32 v74, v23
	v_cvt_pk_fp8_f32 v74, v107, v111
	v_mov_b32_e32 v75, v23
	v_cvt_pk_fp8_f32 v75, v123, v127
	v_cvt_pk_fp8_f32 v74, v115, v119 op_sel:[0,0,1]
	v_cvt_pk_fp8_f32 v75, v131, v135 op_sel:[0,0,1]
	global_store_dwordx4 v[226:227], v[136:139], off
	global_store_dwordx4 v[226:227], v[140:143], off offset:16
	global_store_dwordx4 v[226:227], v[144:147], off offset:32
	global_store_dwordx4 v[226:227], v[72:75], off offset:48
	s_mov_b32 s99, 4
	s_waitcnt vmcnt(20)
	s_andn2_b32 s20, 1, s84
	s_mul_i32 s20, s20, 0xa800
	s_add_i32 s20, s20, 0
	v_add3_u32 v22, s20, v61, v62
	ds_write_b128 v22, v[0:3]
	v_add3_u32 v22, s20, v63, v64
	ds_write_b128 v22, v[4:7]
	v_add3_u32 v22, s20, v65, v66
	ds_write_b128 v22, v[8:11]
	v_add_u32_e32 v22, s20, v20
	v_add3_u32 v48, v22, v67, s63
	v_add3_u32 v22, v22, v68, s63
	ds_write2_b64 v48, v[12:13], v[14:15] offset1:1
	ds_write2_b64 v22, v[16:17], v[18:19] offset1:1
	s_branch .LBB0_1160
.Lp5_st3c:
	s_waitcnt vmcnt(24)
	v_pk_mul_f32 v[72:73], v[72:73], s[98:99] op_sel_hi:[1,0]
	s_waitcnt vmcnt(23)
	v_pk_mul_f32 v[76:77], v[76:77], s[98:99] op_sel_hi:[1,0]
	v_cvt_pk_fp8_f32 v136, v72, v76
	s_waitcnt vmcnt(22)
	v_pk_mul_f32 v[80:81], v[80:81], s[98:99] op_sel_hi:[1,0]
	s_waitcnt vmcnt(21)
	v_pk_mul_f32 v[84:85], v[84:85], s[98:99] op_sel_hi:[1,0]
	s_waitcnt vmcnt(20)
	v_pk_mul_f32 v[88:89], v[88:89], s[98:99] op_sel_hi:[1,0]
	v_cvt_pk_fp8_f32 v136, v80, v84 op_sel:[0,0,1]
	s_waitcnt vmcnt(19)
	v_pk_mul_f32 v[92:93], v[92:93], s[98:99] op_sel_hi:[1,0]
	v_cvt_pk_fp8_f32 v137, v88, v92
	s_waitcnt vmcnt(18)
	v_pk_mul_f32 v[96:97], v[96:97], s[98:99] op_sel_hi:[1,0]
	s_waitcnt vmcnt(17)
	v_pk_mul_f32 v[100:101], v[100:101], s[98:99] op_sel_hi:[1,0]
	v_cvt_pk_fp8_f32 v137, v96, v100 op_sel:[0,0,1]
	s_waitcnt vmcnt(16)
	v_pk_mul_f32 v[104:105], v[104:105], s[98:99] op_sel_hi:[1,0]
	s_waitcnt vmcnt(15)
	v_pk_mul_f32 v[108:109], v[108:109], s[98:99] op_sel_hi:[1,0]
	v_cvt_pk_fp8_f32 v138, v104, v108
	s_waitcnt vmcnt(14)
	v_pk_mul_f32 v[112:113], v[112:113], s[98:99] op_sel_hi:[1,0]
	s_waitcnt vmcnt(13)
	v_pk_mul_f32 v[116:117], v[116:117], s[98:99] op_sel_hi:[1,0]
	s_waitcnt vmcnt(12)
	v_pk_mul_f32 v[120:121], v[120:121], s[98:99] op_sel_hi:[1,0]
	v_cvt_pk_fp8_f32 v138, v112, v116 op_sel:[0,0,1]
	s_waitcnt vmcnt(11)
	v_pk_mul_f32 v[124:125], v[124:125], s[98:99] op_sel_hi:[1,0]
	v_cvt_pk_fp8_f32 v139, v120, v124
	s_waitcnt vmcnt(10)
	v_pk_mul_f32 v[128:129], v[128:129], s[98:99] op_sel_hi:[1,0]
	s_waitcnt vmcnt(9)
	v_pk_mul_f32 v[132:133], v[132:133], s[98:99] op_sel_hi:[1,0]
	v_cvt_pk_fp8_f32 v139, v128, v132 op_sel:[0,0,1]
	v_cvt_pk_fp8_f32 v140, v73, v77
	v_cvt_pk_fp8_f32 v141, v89, v93
	v_cvt_pk_fp8_f32 v141, v97, v101 op_sel:[0,0,1]
	v_cvt_pk_fp8_f32 v142, v105, v109
	v_cvt_pk_fp8_f32 v143, v121, v125
	v_cvt_pk_fp8_f32 v140, v81, v85 op_sel:[0,0,1]
	v_cvt_pk_fp8_f32 v143, v129, v133 op_sel:[0,0,1]
	v_pk_mul_f32 v[74:75], v[74:75], s[98:99] op_sel_hi:[1,0]
	v_pk_mul_f32 v[78:79], v[78:79], s[98:99] op_sel_hi:[1,0]
	v_cvt_pk_fp8_f32 v144, v74, v78
	v_pk_mul_f32 v[90:91], v[90:91], s[98:99] op_sel_hi:[1,0]
	v_pk_mul_f32 v[94:95], v[94:95], s[98:99] op_sel_hi:[1,0]
	v_cvt_pk_fp8_f32 v145, v90, v94
	v_pk_mul_f32 v[98:99], v[98:99], s[98:99] op_sel_hi:[1,0]
	v_pk_mul_f32 v[102:103], v[102:103], s[98:99] op_sel_hi:[1,0]
	v_cvt_pk_fp8_f32 v145, v98, v102 op_sel:[0,0,1]
	v_pk_mul_f32 v[106:107], v[106:107], s[98:99] op_sel_hi:[1,0]
	v_pk_mul_f32 v[110:111], v[110:111], s[98:99] op_sel_hi:[1,0]
	v_cvt_pk_fp8_f32 v146, v106, v110
	v_pk_mul_f32 v[122:123], v[122:123], s[98:99] op_sel_hi:[1,0]
	v_pk_mul_f32 v[126:127], v[126:127], s[98:99] op_sel_hi:[1,0]
	v_cvt_pk_fp8_f32 v147, v122, v126
	v_cvt_pk_fp8_f32 v142, v113, v117 op_sel:[0,0,1]
	v_pk_mul_f32 v[82:83], v[82:83], s[98:99] op_sel_hi:[1,0]
	v_pk_mul_f32 v[86:87], v[86:87], s[98:99] op_sel_hi:[1,0]
	v_cvt_pk_fp8_f32 v144, v82, v86 op_sel:[0,0,1]
	v_pk_mul_f32 v[114:115], v[114:115], s[98:99] op_sel_hi:[1,0]
	v_pk_mul_f32 v[118:119], v[118:119], s[98:99] op_sel_hi:[1,0]
	v_pk_mul_f32 v[130:131], v[130:131], s[98:99] op_sel_hi:[1,0]
	v_pk_mul_f32 v[134:135], v[134:135], s[98:99] op_sel_hi:[1,0]
	v_cvt_pk_fp8_f32 v146, v114, v118 op_sel:[0,0,1]
	v_cvt_pk_fp8_f32 v147, v130, v134 op_sel:[0,0,1]
	v_mov_b32_e32 v72, v23
	v_cvt_pk_fp8_f32 v72, v75, v79
	v_mov_b32_e32 v73, v23
	v_cvt_pk_fp8_f32 v73, v91, v95
	v_cvt_pk_fp8_f32 v72, v83, v87 op_sel:[0,0,1]
	v_cvt_pk_fp8_f32 v73, v99, v103 op_sel:[0,0,1]
	v_mov_b32_e32 v74, v23
	v_cvt_pk_fp8_f32 v74, v107, v111
	v_mov_b32_e32 v75, v23
	v_cvt_pk_fp8_f32 v75, v123, v127
	v_cvt_pk_fp8_f32 v74, v115, v119 op_sel:[0,0,1]
	v_cvt_pk_fp8_f32 v75, v131, v135 op_sel:[0,0,1]
	global_store_dwordx4 v[226:227], v[136:139], off
	global_store_dwordx4 v[226:227], v[140:143], off offset:16
	global_store_dwordx4 v[226:227], v[144:147], off offset:32
	global_store_dwordx4 v[226:227], v[72:75], off offset:48
	s_mov_b32 s99, 0
	s_waitcnt vmcnt(4)
	s_andn2_b32 s20, 1, s84
	s_mul_i32 s20, s20, 0xa800
	s_add_i32 s20, s20, 0
	v_add3_u32 v22, s20, v61, v62
	ds_write_b128 v22, v[0:3]
	v_add3_u32 v22, s20, v63, v64
	ds_write_b128 v22, v[4:7]
	v_add3_u32 v22, s20, v65, v66
	ds_write_b128 v22, v[8:11]
	v_add_u32_e32 v22, s20, v20
	v_add3_u32 v48, v22, v67, s63
	v_add3_u32 v22, v22, v68, s63
	ds_write2_b64 v48, v[12:13], v[14:15] offset1:1
	ds_write2_b64 v22, v[16:17], v[18:19] offset1:1
	s_branch .LBB0_1160

.Lp5_i4_1168:
	s_lshl_b64 s[44:45], s[44:45], 2
	s_waitcnt lgkmcnt(0)
	s_add_u32 s20, s42, s44
	s_addc_u32 s43, s43, s45
	s_bfe_u32 s44, s53, 0x70003
	s_lshl_b32 s42, s44, 17
	s_add_u32 s42, s20, s42
	s_addc_u32 s43, s43, 0
	v_lshlrev_b32_e32 v22, 2, v22
	v_lshl_add_u64 v[230:231], s[42:43], 0, v[22:23]
	global_load_dwordx4 v[72:75], v22, s[42:43] nt
	s_nop 0
	v_mov_b32_e32 v136, v23
	v_mov_b32_e32 v137, v23
	v_mov_b32_e32 v138, v23
	v_mov_b32_e32 v139, v23
	v_mov_b32_e32 v140, v23
	v_mov_b32_e32 v141, v23
	v_mov_b32_e32 v142, v23
	v_mov_b32_e32 v143, v23
	v_mov_b32_e32 v144, v23
	v_mov_b32_e32 v145, v23
	v_mov_b32_e32 v146, v23
	v_mov_b32_e32 v147, v23
	s_mul_i32 s20, s40, s44
	v_ashrrev_i32_e32 v227, 31, v226
	v_lshl_add_u64 v[226:227], s[20:21], 0, v[226:227]
	v_lshl_add_u64 v[226:227], v[226:227], 4, s[38:39]
	s_mov_b32 s98, s41
	s_addk_i32 s53, 0x400
	s_waitcnt vmcnt(25)
	v_add_co_u32_e32 v76, vcc, s64, v230
	v_addc_co_u32_e32 v77, vcc, 0, v231, vcc
	global_load_dwordx4 v[76:79], v[76:77], off nt
	s_nop 0
	v_pk_mul_f32 v[148:149], v[148:149], s[100:101] op_sel_hi:[1,0]
	s_waitcnt vmcnt(25)
	v_add_co_u32_e32 v80, vcc, s65, v230
	v_addc_co_u32_e32 v81, vcc, 0, v231, vcc
	global_load_dwordx4 v[80:83], v[80:81], off nt
	s_nop 0
	v_pk_mul_f32 v[152:153], v[152:153], s[100:101] op_sel_hi:[1,0]
	v_cvt_pk_fp8_f32 v212, v148, v152
	s_waitcnt vmcnt(25)
	v_add_co_u32_e32 v84, vcc, s66, v230
	v_addc_co_u32_e32 v85, vcc, 0, v231, vcc
	global_load_dwordx4 v[84:87], v[84:85], off nt
	s_nop 0
	v_pk_mul_f32 v[156:157], v[156:157], s[100:101] op_sel_hi:[1,0]
	s_waitcnt vmcnt(25)
	v_add_co_u32_e32 v88, vcc, s67, v230
	v_addc_co_u32_e32 v89, vcc, 0, v231, vcc
	global_load_dwordx4 v[88:91], v[88:89], off nt
	s_nop 0
	v_pk_mul_f32 v[160:161], v[160:161], s[100:101] op_sel_hi:[1,0]
	s_waitcnt vmcnt(25)
	v_add_co_u32_e32 v92, vcc, s68, v230
	v_addc_co_u32_e32 v93, vcc, 0, v231, vcc
	global_load_dwordx4 v[92:95], v[92:93], off nt
	s_nop 0
	v_pk_mul_f32 v[164:165], v[164:165], s[100:101] op_sel_hi:[1,0]
	v_cvt_pk_fp8_f32 v212, v156, v160 op_sel:[0,0,1]
	s_waitcnt vmcnt(25)
	v_add_co_u32_e32 v96, vcc, s69, v230
	v_addc_co_u32_e32 v97, vcc, 0, v231, vcc
	global_load_dwordx4 v[96:99], v[96:97], off nt
	s_nop 0
	v_pk_mul_f32 v[168:169], v[168:169], s[100:101] op_sel_hi:[1,0]
	v_cvt_pk_fp8_f32 v213, v164, v168
	s_waitcnt vmcnt(25)
	v_add_co_u32_e32 v100, vcc, s70, v230
	v_addc_co_u32_e32 v101, vcc, 0, v231, vcc
	global_load_dwordx4 v[100:103], v[100:101], off nt
	s_nop 0
	v_pk_mul_f32 v[172:173], v[172:173], s[100:101] op_sel_hi:[1,0]
	s_waitcnt vmcnt(25)
	v_add_co_u32_e32 v104, vcc, s71, v230
	v_addc_co_u32_e32 v105, vcc, 0, v231, vcc
	global_load_dwordx4 v[104:107], v[104:105], off nt
	s_nop 0
	v_pk_mul_f32 v[176:177], v[176:177], s[100:101] op_sel_hi:[1,0]
	v_cvt_pk_fp8_f32 v213, v172, v176 op_sel:[0,0,1]
	s_waitcnt vmcnt(25)
	v_add_co_u32_e32 v108, vcc, s72, v230
	v_addc_co_u32_e32 v109, vcc, 0, v231, vcc
	global_load_dwordx4 v[108:111], v[108:109], off nt
	s_nop 0
	v_pk_mul_f32 v[180:181], v[180:181], s[100:101] op_sel_hi:[1,0]
	s_waitcnt vmcnt(25)
	v_add_co_u32_e32 v112, vcc, s73, v230
	v_addc_co_u32_e32 v113, vcc, 0, v231, vcc
	global_load_dwordx4 v[112:115], v[112:113], off nt
	s_nop 0
	v_pk_mul_f32 v[184:185], v[184:185], s[100:101] op_sel_hi:[1,0]
	v_cvt_pk_fp8_f32 v214, v180, v184
	s_waitcnt vmcnt(25)
	v_add_co_u32_e32 v116, vcc, s74, v230
	v_addc_co_u32_e32 v117, vcc, 0, v231, vcc
	global_load_dwordx4 v[116:119], v[116:117], off nt
	s_nop 0
	v_pk_mul_f32 v[188:189], v[188:189], s[100:101] op_sel_hi:[1,0]
	s_waitcnt vmcnt(25)
	v_add_co_u32_e32 v120, vcc, s75, v230
	v_addc_co_u32_e32 v121, vcc, 0, v231, vcc
	global_load_dwordx4 v[120:123], v[120:121], off nt
	s_nop 0
	v_pk_mul_f32 v[192:193], v[192:193], s[100:101] op_sel_hi:[1,0]
	s_waitcnt vmcnt(25)
	v_add_co_u32_e32 v124, vcc, s76, v230
	v_addc_co_u32_e32 v125, vcc, 0, v231, vcc
	global_load_dwordx4 v[124:127], v[124:125], off nt
	s_nop 0
	v_pk_mul_f32 v[196:197], v[196:197], s[100:101] op_sel_hi:[1,0]
	v_cvt_pk_fp8_f32 v214, v188, v192 op_sel:[0,0,1]
	s_waitcnt vmcnt(25)
	v_add_co_u32_e32 v128, vcc, s77, v230
	v_addc_co_u32_e32 v129, vcc, 0, v231, vcc
	global_load_dwordx4 v[128:131], v[128:129], off nt
	s_nop 0
	v_pk_mul_f32 v[200:201], v[200:201], s[100:101] op_sel_hi:[1,0]
	v_cvt_pk_fp8_f32 v215, v196, v200
	s_waitcnt vmcnt(25)
	v_add_co_u32_e32 v132, vcc, s78, v230
	v_addc_co_u32_e32 v133, vcc, 0, v231, vcc
	global_load_dwordx4 v[132:135], v[132:133], off nt
	s_nop 0
	v_pk_mul_f32 v[204:205], v[204:205], s[100:101] op_sel_hi:[1,0]
	s_waitcnt vmcnt(25)
	v_pk_mul_f32 v[208:209], v[208:209], s[100:101] op_sel_hi:[1,0]
	v_cvt_pk_fp8_f32 v215, v204, v208 op_sel:[0,0,1]
	v_cvt_pk_fp8_f32 v216, v149, v153
	v_cvt_pk_fp8_f32 v217, v165, v169
	v_cvt_pk_fp8_f32 v217, v173, v177 op_sel:[0,0,1]
	v_cvt_pk_fp8_f32 v218, v181, v185
	v_cvt_pk_fp8_f32 v219, v197, v201
	v_cvt_pk_fp8_f32 v216, v157, v161 op_sel:[0,0,1]
	v_cvt_pk_fp8_f32 v219, v205, v209 op_sel:[0,0,1]
	v_pk_mul_f32 v[150:151], v[150:151], s[100:101] op_sel_hi:[1,0]
	v_pk_mul_f32 v[154:155], v[154:155], s[100:101] op_sel_hi:[1,0]
	v_cvt_pk_fp8_f32 v220, v150, v154
	v_pk_mul_f32 v[166:167], v[166:167], s[100:101] op_sel_hi:[1,0]
	v_pk_mul_f32 v[170:171], v[170:171], s[100:101] op_sel_hi:[1,0]
	v_cvt_pk_fp8_f32 v221, v166, v170
	v_pk_mul_f32 v[174:175], v[174:175], s[100:101] op_sel_hi:[1,0]
	v_pk_mul_f32 v[178:179], v[178:179], s[100:101] op_sel_hi:[1,0]
	v_cvt_pk_fp8_f32 v221, v174, v178 op_sel:[0,0,1]
	v_pk_mul_f32 v[182:183], v[182:183], s[100:101] op_sel_hi:[1,0]
	v_pk_mul_f32 v[186:187], v[186:187], s[100:101] op_sel_hi:[1,0]
	v_cvt_pk_fp8_f32 v222, v182, v186
	v_pk_mul_f32 v[198:199], v[198:199], s[100:101] op_sel_hi:[1,0]
	v_pk_mul_f32 v[202:203], v[202:203], s[100:101] op_sel_hi:[1,0]
	v_cvt_pk_fp8_f32 v223, v198, v202
	v_cvt_pk_fp8_f32 v218, v189, v193 op_sel:[0,0,1]
	v_pk_mul_f32 v[158:159], v[158:159], s[100:101] op_sel_hi:[1,0]
	v_pk_mul_f32 v[162:163], v[162:163], s[100:101] op_sel_hi:[1,0]
	v_cvt_pk_fp8_f32 v220, v158, v162 op_sel:[0,0,1]
	v_pk_mul_f32 v[190:191], v[190:191], s[100:101] op_sel_hi:[1,0]
	v_pk_mul_f32 v[194:195], v[194:195], s[100:101] op_sel_hi:[1,0]
	v_pk_mul_f32 v[206:207], v[206:207], s[100:101] op_sel_hi:[1,0]
	v_pk_mul_f32 v[210:211], v[210:211], s[100:101] op_sel_hi:[1,0]
	v_cvt_pk_fp8_f32 v222, v190, v194 op_sel:[0,0,1]
	v_cvt_pk_fp8_f32 v223, v206, v210 op_sel:[0,0,1]
	v_mov_b32_e32 v148, v23
	v_cvt_pk_fp8_f32 v148, v151, v155
	v_mov_b32_e32 v149, v23
	v_cvt_pk_fp8_f32 v149, v167, v171
	v_cvt_pk_fp8_f32 v148, v159, v163 op_sel:[0,0,1]
	v_cvt_pk_fp8_f32 v149, v175, v179 op_sel:[0,0,1]
	v_mov_b32_e32 v150, v23
	v_cvt_pk_fp8_f32 v150, v183, v187
	v_mov_b32_e32 v151, v23
	v_cvt_pk_fp8_f32 v151, v199, v203
	v_cvt_pk_fp8_f32 v150, v191, v195 op_sel:[0,0,1]
	v_cvt_pk_fp8_f32 v151, v207, v211 op_sel:[0,0,1]
	global_store_dwordx4 v[228:229], v[212:215], off
	global_store_dwordx4 v[228:229], v[216:219], off offset:16
	global_store_dwordx4 v[228:229], v[220:223], off offset:32
	global_store_dwordx4 v[228:229], v[148:151], off offset:48
	s_mov_b32 s99, 3
	s_waitcnt vmcnt(20)
	s_andn2_b32 s20, 1, s84
	s_mul_i32 s20, s20, 0xa800
	s_add_i32 s20, s20, 0
	v_add3_u32 v22, s20, v61, v62
	ds_write_b128 v22, v[0:3]
	v_add3_u32 v22, s20, v63, v64
	ds_write_b128 v22, v[4:7]
	v_add3_u32 v22, s20, v65, v66
	ds_write_b128 v22, v[8:11]
	v_add_u32_e32 v22, s20, v20
	v_add3_u32 v48, v22, v67, s63
	v_add3_u32 v22, v22, v68, s63
	ds_write2_b64 v48, v[12:13], v[14:15] offset1:1
	ds_write2_b64 v22, v[16:17], v[18:19] offset1:1
	s_branch .LBB0_1160
.Lp5_st4c:
	s_waitcnt vmcnt(24)
	v_pk_mul_f32 v[148:149], v[148:149], s[100:101] op_sel_hi:[1,0]
	s_waitcnt vmcnt(23)
	v_pk_mul_f32 v[152:153], v[152:153], s[100:101] op_sel_hi:[1,0]
	v_cvt_pk_fp8_f32 v212, v148, v152
	s_waitcnt vmcnt(22)
	v_pk_mul_f32 v[156:157], v[156:157], s[100:101] op_sel_hi:[1,0]
	s_waitcnt vmcnt(21)
	v_pk_mul_f32 v[160:161], v[160:161], s[100:101] op_sel_hi:[1,0]
	s_waitcnt vmcnt(20)
	v_pk_mul_f32 v[164:165], v[164:165], s[100:101] op_sel_hi:[1,0]
	v_cvt_pk_fp8_f32 v212, v156, v160 op_sel:[0,0,1]
	s_waitcnt vmcnt(19)
	v_pk_mul_f32 v[168:169], v[168:169], s[100:101] op_sel_hi:[1,0]
	v_cvt_pk_fp8_f32 v213, v164, v168
	s_waitcnt vmcnt(18)
	v_pk_mul_f32 v[172:173], v[172:173], s[100:101] op_sel_hi:[1,0]
	s_waitcnt vmcnt(17)
	v_pk_mul_f32 v[176:177], v[176:177], s[100:101] op_sel_hi:[1,0]
	v_cvt_pk_fp8_f32 v213, v172, v176 op_sel:[0,0,1]
	s_waitcnt vmcnt(16)
	v_pk_mul_f32 v[180:181], v[180:181], s[100:101] op_sel_hi:[1,0]
	s_waitcnt vmcnt(15)
	v_pk_mul_f32 v[184:185], v[184:185], s[100:101] op_sel_hi:[1,0]
	v_cvt_pk_fp8_f32 v214, v180, v184
	s_waitcnt vmcnt(14)
	v_pk_mul_f32 v[188:189], v[188:189], s[100:101] op_sel_hi:[1,0]
	s_waitcnt vmcnt(13)
	v_pk_mul_f32 v[192:193], v[192:193], s[100:101] op_sel_hi:[1,0]
	s_waitcnt vmcnt(12)
	v_pk_mul_f32 v[196:197], v[196:197], s[100:101] op_sel_hi:[1,0]
	v_cvt_pk_fp8_f32 v214, v188, v192 op_sel:[0,0,1]
	s_waitcnt vmcnt(11)
	v_pk_mul_f32 v[200:201], v[200:201], s[100:101] op_sel_hi:[1,0]
	v_cvt_pk_fp8_f32 v215, v196, v200
	s_waitcnt vmcnt(10)
	v_pk_mul_f32 v[204:205], v[204:205], s[100:101] op_sel_hi:[1,0]
	s_waitcnt vmcnt(9)
	v_pk_mul_f32 v[208:209], v[208:209], s[100:101] op_sel_hi:[1,0]
	v_cvt_pk_fp8_f32 v215, v204, v208 op_sel:[0,0,1]
	v_cvt_pk_fp8_f32 v216, v149, v153
	v_cvt_pk_fp8_f32 v217, v165, v169
	v_cvt_pk_fp8_f32 v217, v173, v177 op_sel:[0,0,1]
	v_cvt_pk_fp8_f32 v218, v181, v185
	v_cvt_pk_fp8_f32 v219, v197, v201
	v_cvt_pk_fp8_f32 v216, v157, v161 op_sel:[0,0,1]
	v_cvt_pk_fp8_f32 v219, v205, v209 op_sel:[0,0,1]
	v_pk_mul_f32 v[150:151], v[150:151], s[100:101] op_sel_hi:[1,0]
	v_pk_mul_f32 v[154:155], v[154:155], s[100:101] op_sel_hi:[1,0]
	v_cvt_pk_fp8_f32 v220, v150, v154
	v_pk_mul_f32 v[166:167], v[166:167], s[100:101] op_sel_hi:[1,0]
	v_pk_mul_f32 v[170:171], v[170:171], s[100:101] op_sel_hi:[1,0]
	v_cvt_pk_fp8_f32 v221, v166, v170
	v_pk_mul_f32 v[174:175], v[174:175], s[100:101] op_sel_hi:[1,0]
	v_pk_mul_f32 v[178:179], v[178:179], s[100:101] op_sel_hi:[1,0]
	v_cvt_pk_fp8_f32 v221, v174, v178 op_sel:[0,0,1]
	v_pk_mul_f32 v[182:183], v[182:183], s[100:101] op_sel_hi:[1,0]
	v_pk_mul_f32 v[186:187], v[186:187], s[100:101] op_sel_hi:[1,0]
	v_cvt_pk_fp8_f32 v222, v182, v186
	v_pk_mul_f32 v[198:199], v[198:199], s[100:101] op_sel_hi:[1,0]
	v_pk_mul_f32 v[202:203], v[202:203], s[100:101] op_sel_hi:[1,0]
	v_cvt_pk_fp8_f32 v223, v198, v202
	v_cvt_pk_fp8_f32 v218, v189, v193 op_sel:[0,0,1]
	v_pk_mul_f32 v[158:159], v[158:159], s[100:101] op_sel_hi:[1,0]
	v_pk_mul_f32 v[162:163], v[162:163], s[100:101] op_sel_hi:[1,0]
	v_cvt_pk_fp8_f32 v220, v158, v162 op_sel:[0,0,1]
	v_pk_mul_f32 v[190:191], v[190:191], s[100:101] op_sel_hi:[1,0]
	v_pk_mul_f32 v[194:195], v[194:195], s[100:101] op_sel_hi:[1,0]
	v_pk_mul_f32 v[206:207], v[206:207], s[100:101] op_sel_hi:[1,0]
	v_pk_mul_f32 v[210:211], v[210:211], s[100:101] op_sel_hi:[1,0]
	v_cvt_pk_fp8_f32 v222, v190, v194 op_sel:[0,0,1]
	v_cvt_pk_fp8_f32 v223, v206, v210 op_sel:[0,0,1]
	v_mov_b32_e32 v148, v23
	v_cvt_pk_fp8_f32 v148, v151, v155
	v_mov_b32_e32 v149, v23
	v_cvt_pk_fp8_f32 v149, v167, v171
	v_cvt_pk_fp8_f32 v148, v159, v163 op_sel:[0,0,1]
	v_cvt_pk_fp8_f32 v149, v175, v179 op_sel:[0,0,1]
	v_mov_b32_e32 v150, v23
	v_cvt_pk_fp8_f32 v150, v183, v187
	v_mov_b32_e32 v151, v23
	v_cvt_pk_fp8_f32 v151, v199, v203
	v_cvt_pk_fp8_f32 v150, v191, v195 op_sel:[0,0,1]
	v_cvt_pk_fp8_f32 v151, v207, v211 op_sel:[0,0,1]
	global_store_dwordx4 v[228:229], v[212:215], off
	global_store_dwordx4 v[228:229], v[216:219], off offset:16
	global_store_dwordx4 v[228:229], v[220:223], off offset:32
	global_store_dwordx4 v[228:229], v[148:151], off offset:48
	s_mov_b32 s99, 0
	s_waitcnt vmcnt(4)
	s_andn2_b32 s20, 1, s84
	s_mul_i32 s20, s20, 0xa800
	s_add_i32 s20, s20, 0
	v_add3_u32 v22, s20, v61, v62
	ds_write_b128 v22, v[0:3]
	v_add3_u32 v22, s20, v63, v64
	ds_write_b128 v22, v[4:7]
	v_add3_u32 v22, s20, v65, v66
	ds_write_b128 v22, v[8:11]
	v_add_u32_e32 v22, s20, v20
	v_add3_u32 v48, v22, v67, s63
	v_add3_u32 v22, v22, v68, s63
	ds_write2_b64 v48, v[12:13], v[14:15] offset1:1
	ds_write2_b64 v22, v[16:17], v[18:19] offset1:1
	s_branch .LBB0_1160

.Lp13_i2_2384:
	s_lshl_b64 s[24:25], s[24:25], 2
	s_waitcnt lgkmcnt(0)
	s_add_u32 s12, s22, s24
	s_addc_u32 s23, s23, s25
	s_bfe_u32 s24, s3, 0x70003
	s_lshl_b32 s22, s24, 17
	s_add_u32 s22, s12, s22
	s_addc_u32 s23, s23, 0
	v_lshlrev_b32_e32 v192, 2, v192
	v_lshl_add_u64 v[232:233], s[22:23], 0, v[192:193]
	global_load_dwordx4 v[116:119], v192, s[22:23] nt
	s_nop 0
	v_mov_b32_e32 v180, v11
	v_mov_b32_e32 v181, v11
	v_mov_b32_e32 v182, v11
	v_mov_b32_e32 v183, v11
	v_mov_b32_e32 v184, v11
	v_mov_b32_e32 v185, v11
	v_mov_b32_e32 v186, v11
	v_mov_b32_e32 v187, v11
	v_mov_b32_e32 v188, v11
	v_mov_b32_e32 v189, v11
	v_mov_b32_e32 v190, v11
	v_mov_b32_e32 v191, v11
	s_mul_i32 s12, s20, s24
	v_ashrrev_i32_e32 v229, 31, v228
	v_lshl_add_u64 v[228:229], s[12:13], 0, v[228:229]
	v_lshl_add_u64 v[228:229], v[228:229], 4, s[18:19]
	s_mov_b32 s100, s21
	s_addk_i32 s3, 0x400
	s_waitcnt vmcnt(18)
	v_add_co_u32_e32 v120, vcc, s35, v232
	v_addc_co_u32_e32 v121, vcc, 0, v233, vcc
	global_load_dwordx4 v[120:123], v[120:121], off nt
	s_nop 0
	v_pk_mul_f32 v[40:41], v[40:41], s[98:99] op_sel_hi:[1,0]
	s_waitcnt vmcnt(18)
	v_add_co_u32_e32 v124, vcc, s36, v232
	v_addc_co_u32_e32 v125, vcc, 0, v233, vcc
	global_load_dwordx4 v[124:127], v[124:125], off nt
	s_nop 0
	v_pk_mul_f32 v[44:45], v[44:45], s[98:99] op_sel_hi:[1,0]
	v_cvt_pk_fp8_f32 v104, v40, v44
	s_waitcnt vmcnt(18)
	v_add_co_u32_e32 v128, vcc, s37, v232
	v_addc_co_u32_e32 v129, vcc, 0, v233, vcc
	global_load_dwordx4 v[128:131], v[128:129], off nt
	s_nop 0
	v_pk_mul_f32 v[48:49], v[48:49], s[98:99] op_sel_hi:[1,0]
	s_waitcnt vmcnt(18)
	v_add_co_u32_e32 v132, vcc, s38, v232
	v_addc_co_u32_e32 v133, vcc, 0, v233, vcc
	global_load_dwordx4 v[132:135], v[132:133], off nt
	s_nop 0
	v_pk_mul_f32 v[52:53], v[52:53], s[98:99] op_sel_hi:[1,0]
	s_waitcnt vmcnt(18)
	v_add_co_u32_e32 v136, vcc, s39, v232
	v_addc_co_u32_e32 v137, vcc, 0, v233, vcc
	global_load_dwordx4 v[136:139], v[136:137], off nt
	s_nop 0
	v_pk_mul_f32 v[56:57], v[56:57], s[98:99] op_sel_hi:[1,0]
	v_cvt_pk_fp8_f32 v104, v48, v52 op_sel:[0,0,1]
	s_waitcnt vmcnt(18)
	v_add_co_u32_e32 v140, vcc, s40, v232
	v_addc_co_u32_e32 v141, vcc, 0, v233, vcc
	global_load_dwordx4 v[140:143], v[140:141], off nt
	s_nop 0
	v_pk_mul_f32 v[60:61], v[60:61], s[98:99] op_sel_hi:[1,0]
	v_cvt_pk_fp8_f32 v105, v56, v60
	s_waitcnt vmcnt(18)
	v_add_co_u32_e32 v144, vcc, s41, v232
	v_addc_co_u32_e32 v145, vcc, 0, v233, vcc
	global_load_dwordx4 v[144:147], v[144:145], off nt
	s_nop 0
	v_pk_mul_f32 v[64:65], v[64:65], s[98:99] op_sel_hi:[1,0]
	s_waitcnt vmcnt(18)
	v_add_co_u32_e32 v148, vcc, s42, v232
	v_addc_co_u32_e32 v149, vcc, 0, v233, vcc
	global_load_dwordx4 v[148:151], v[148:149], off nt
	s_nop 0
	v_pk_mul_f32 v[68:69], v[68:69], s[98:99] op_sel_hi:[1,0]
	v_cvt_pk_fp8_f32 v105, v64, v68 op_sel:[0,0,1]
	s_waitcnt vmcnt(18)
	v_add_co_u32_e32 v152, vcc, s43, v232
	v_addc_co_u32_e32 v153, vcc, 0, v233, vcc
	global_load_dwordx4 v[152:155], v[152:153], off nt
	s_nop 0
	v_pk_mul_f32 v[72:73], v[72:73], s[98:99] op_sel_hi:[1,0]
	s_waitcnt vmcnt(18)
	v_add_co_u32_e32 v156, vcc, s44, v232
	v_addc_co_u32_e32 v157, vcc, 0, v233, vcc
	global_load_dwordx4 v[156:159], v[156:157], off nt
	s_nop 0
	v_pk_mul_f32 v[76:77], v[76:77], s[98:99] op_sel_hi:[1,0]
	v_cvt_pk_fp8_f32 v106, v72, v76
	s_waitcnt vmcnt(18)
	v_add_co_u32_e32 v160, vcc, s45, v232
	v_addc_co_u32_e32 v161, vcc, 0, v233, vcc
	global_load_dwordx4 v[160:163], v[160:161], off nt
	s_nop 0
	v_pk_mul_f32 v[80:81], v[80:81], s[98:99] op_sel_hi:[1,0]
	s_waitcnt vmcnt(18)
	v_add_co_u32_e32 v164, vcc, s46, v232
	v_addc_co_u32_e32 v165, vcc, 0, v233, vcc
	global_load_dwordx4 v[164:167], v[164:165], off nt
	s_nop 0
	v_pk_mul_f32 v[84:85], v[84:85], s[98:99] op_sel_hi:[1,0]
	s_waitcnt vmcnt(18)
	v_add_co_u32_e32 v168, vcc, s47, v232
	v_addc_co_u32_e32 v169, vcc, 0, v233, vcc
	global_load_dwordx4 v[168:171], v[168:169], off nt
	s_nop 0
	v_pk_mul_f32 v[88:89], v[88:89], s[98:99] op_sel_hi:[1,0]
	v_cvt_pk_fp8_f32 v106, v80, v84 op_sel:[0,0,1]
	v_pk_mul_f32 v[82:83], v[82:83], s[98:99] op_sel_hi:[1,0]
	s_waitcnt vmcnt(18)
	v_add_co_u32_e32 v172, vcc, s48, v232
	v_addc_co_u32_e32 v173, vcc, 0, v233, vcc
	global_load_dwordx4 v[172:175], v[172:173], off nt
	s_nop 0
	v_pk_mul_f32 v[92:93], v[92:93], s[98:99] op_sel_hi:[1,0]
	v_cvt_pk_fp8_f32 v107, v88, v92
	s_waitcnt vmcnt(18)
	v_add_co_u32_e32 v176, vcc, s49, v232
	v_addc_co_u32_e32 v177, vcc, 0, v233, vcc
	global_load_dwordx4 v[176:179], v[176:177], off nt
	s_nop 0
	v_pk_mul_f32 v[96:97], v[96:97], s[98:99] op_sel_hi:[1,0]
	s_waitcnt vmcnt(18)
	v_pk_mul_f32 v[100:101], v[100:101], s[98:99] op_sel_hi:[1,0]
	v_cvt_pk_fp8_f32 v107, v96, v100 op_sel:[0,0,1]
	v_cvt_pk_fp8_f32 v108, v41, v45
	v_cvt_pk_fp8_f32 v109, v57, v61
	v_cvt_pk_fp8_f32 v109, v65, v69 op_sel:[0,0,1]
	v_cvt_pk_fp8_f32 v110, v73, v77
	v_cvt_pk_fp8_f32 v111, v89, v93
	v_cvt_pk_fp8_f32 v108, v49, v53 op_sel:[0,0,1]
	v_cvt_pk_fp8_f32 v111, v97, v101 op_sel:[0,0,1]
	v_pk_mul_f32 v[42:43], v[42:43], s[98:99] op_sel_hi:[1,0]
	v_pk_mul_f32 v[46:47], v[46:47], s[98:99] op_sel_hi:[1,0]
	v_cvt_pk_fp8_f32 v112, v42, v46
	v_pk_mul_f32 v[58:59], v[58:59], s[98:99] op_sel_hi:[1,0]
	v_pk_mul_f32 v[62:63], v[62:63], s[98:99] op_sel_hi:[1,0]
	v_cvt_pk_fp8_f32 v113, v58, v62
	v_pk_mul_f32 v[66:67], v[66:67], s[98:99] op_sel_hi:[1,0]
	v_pk_mul_f32 v[70:71], v[70:71], s[98:99] op_sel_hi:[1,0]
	v_cvt_pk_fp8_f32 v113, v66, v70 op_sel:[0,0,1]
	v_pk_mul_f32 v[74:75], v[74:75], s[98:99] op_sel_hi:[1,0]
	v_pk_mul_f32 v[78:79], v[78:79], s[98:99] op_sel_hi:[1,0]
	v_cvt_pk_fp8_f32 v114, v74, v78
	v_pk_mul_f32 v[90:91], v[90:91], s[98:99] op_sel_hi:[1,0]
	v_pk_mul_f32 v[94:95], v[94:95], s[98:99] op_sel_hi:[1,0]
	v_cvt_pk_fp8_f32 v115, v90, v94
	v_cvt_pk_fp8_f32 v110, v81, v85 op_sel:[0,0,1]
	v_pk_mul_f32 v[50:51], v[50:51], s[98:99] op_sel_hi:[1,0]
	v_pk_mul_f32 v[54:55], v[54:55], s[98:99] op_sel_hi:[1,0]
	v_cvt_pk_fp8_f32 v112, v50, v54 op_sel:[0,0,1]
	v_pk_mul_f32 v[86:87], v[86:87], s[98:99] op_sel_hi:[1,0]
	v_pk_mul_f32 v[98:99], v[98:99], s[98:99] op_sel_hi:[1,0]
	v_pk_mul_f32 v[102:103], v[102:103], s[98:99] op_sel_hi:[1,0]
	v_cvt_pk_fp8_f32 v114, v82, v86 op_sel:[0,0,1]
	v_cvt_pk_fp8_f32 v115, v98, v102 op_sel:[0,0,1]
	v_mov_b32_e32 v40, v11
	v_cvt_pk_fp8_f32 v40, v43, v47
	v_mov_b32_e32 v41, v11
	v_cvt_pk_fp8_f32 v41, v59, v63
	v_cvt_pk_fp8_f32 v40, v51, v55 op_sel:[0,0,1]
	v_cvt_pk_fp8_f32 v41, v67, v71 op_sel:[0,0,1]
	v_mov_b32_e32 v42, v11
	v_cvt_pk_fp8_f32 v42, v75, v79
	v_mov_b32_e32 v43, v11
	v_cvt_pk_fp8_f32 v43, v91, v95
	v_cvt_pk_fp8_f32 v42, v83, v87 op_sel:[0,0,1]
	v_cvt_pk_fp8_f32 v43, v99, v103 op_sel:[0,0,1]
	global_store_dwordx4 v[226:227], v[104:107], off
	global_store_dwordx4 v[226:227], v[108:111], off offset:16
	global_store_dwordx4 v[226:227], v[112:115], off offset:32
	global_store_dwordx4 v[226:227], v[40:43], off offset:48
	s_mov_b32 s99, 4
	s_waitcnt vmcnt(20)
	s_andn2_b32 s12, 1, s64
	s_mulk_i32 s12, 0x4600
	s_add_i32 s12, s12, 0
	v_add_u32_e32 v10, s12, v33
	v_add3_u32 v22, s12, v31, v32
	v_add3_u32 v10, v10, v34, s34
	ds_write_b128 v22, v[0:3]
	ds_write2_b64 v10, v[4:5], v[6:7] offset1:1
	s_branch .LBB0_2376
.Lp13_st1c:
	s_waitcnt vmcnt(17)
	v_pk_mul_f32 v[40:41], v[40:41], s[98:99] op_sel_hi:[1,0]
	s_waitcnt vmcnt(16)
	v_pk_mul_f32 v[44:45], v[44:45], s[98:99] op_sel_hi:[1,0]
	v_cvt_pk_fp8_f32 v104, v40, v44
	s_waitcnt vmcnt(15)
	v_pk_mul_f32 v[48:49], v[48:49], s[98:99] op_sel_hi:[1,0]
	s_waitcnt vmcnt(14)
	v_pk_mul_f32 v[52:53], v[52:53], s[98:99] op_sel_hi:[1,0]
	s_waitcnt vmcnt(13)
	v_pk_mul_f32 v[56:57], v[56:57], s[98:99] op_sel_hi:[1,0]
	v_cvt_pk_fp8_f32 v104, v48, v52 op_sel:[0,0,1]
	s_waitcnt vmcnt(12)
	v_pk_mul_f32 v[60:61], v[60:61], s[98:99] op_sel_hi:[1,0]
	v_cvt_pk_fp8_f32 v105, v56, v60
	s_waitcnt vmcnt(11)
	v_pk_mul_f32 v[64:65], v[64:65], s[98:99] op_sel_hi:[1,0]
	s_waitcnt vmcnt(10)
	v_pk_mul_f32 v[68:69], v[68:69], s[98:99] op_sel_hi:[1,0]
	v_cvt_pk_fp8_f32 v105, v64, v68 op_sel:[0,0,1]
	s_waitcnt vmcnt(9)
	v_pk_mul_f32 v[72:73], v[72:73], s[98:99] op_sel_hi:[1,0]
	s_waitcnt vmcnt(8)
	v_pk_mul_f32 v[76:77], v[76:77], s[98:99] op_sel_hi:[1,0]
	v_cvt_pk_fp8_f32 v106, v72, v76
	s_waitcnt vmcnt(7)
	v_pk_mul_f32 v[80:81], v[80:81], s[98:99] op_sel_hi:[1,0]
	s_waitcnt vmcnt(6)
	v_pk_mul_f32 v[84:85], v[84:85], s[98:99] op_sel_hi:[1,0]
	s_waitcnt vmcnt(5)
	v_pk_mul_f32 v[88:89], v[88:89], s[98:99] op_sel_hi:[1,0]
	v_cvt_pk_fp8_f32 v106, v80, v84 op_sel:[0,0,1]
	v_pk_mul_f32 v[82:83], v[82:83], s[98:99] op_sel_hi:[1,0]
	s_waitcnt vmcnt(4)
	v_pk_mul_f32 v[92:93], v[92:93], s[98:99] op_sel_hi:[1,0]
	v_cvt_pk_fp8_f32 v107, v88, v92
	s_waitcnt vmcnt(3)
	v_pk_mul_f32 v[96:97], v[96:97], s[98:99] op_sel_hi:[1,0]
	s_waitcnt vmcnt(2)
	v_pk_mul_f32 v[100:101], v[100:101], s[98:99] op_sel_hi:[1,0]
	v_cvt_pk_fp8_f32 v107, v96, v100 op_sel:[0,0,1]
	v_cvt_pk_fp8_f32 v108, v41, v45
	v_cvt_pk_fp8_f32 v109, v57, v61
	v_cvt_pk_fp8_f32 v109, v65, v69 op_sel:[0,0,1]
	v_cvt_pk_fp8_f32 v110, v73, v77
	v_cvt_pk_fp8_f32 v111, v89, v93
	v_cvt_pk_fp8_f32 v108, v49, v53 op_sel:[0,0,1]
	v_cvt_pk_fp8_f32 v111, v97, v101 op_sel:[0,0,1]
	v_pk_mul_f32 v[42:43], v[42:43], s[98:99] op_sel_hi:[1,0]
	v_pk_mul_f32 v[46:47], v[46:47], s[98:99] op_sel_hi:[1,0]
	v_cvt_pk_fp8_f32 v112, v42, v46
	v_pk_mul_f32 v[58:59], v[58:59], s[98:99] op_sel_hi:[1,0]
	v_pk_mul_f32 v[62:63], v[62:63], s[98:99] op_sel_hi:[1,0]
	v_cvt_pk_fp8_f32 v113, v58, v62
	v_pk_mul_f32 v[66:67], v[66:67], s[98:99] op_sel_hi:[1,0]
	v_pk_mul_f32 v[70:71], v[70:71], s[98:99] op_sel_hi:[1,0]
	v_cvt_pk_fp8_f32 v113, v66, v70 op_sel:[0,0,1]
	v_pk_mul_f32 v[74:75], v[74:75], s[98:99] op_sel_hi:[1,0]
	v_pk_mul_f32 v[78:79], v[78:79], s[98:99] op_sel_hi:[1,0]
	v_cvt_pk_fp8_f32 v114, v74, v78
	v_pk_mul_f32 v[90:91], v[90:91], s[98:99] op_sel_hi:[1,0]
	v_pk_mul_f32 v[94:95], v[94:95], s[98:99] op_sel_hi:[1,0]
	v_cvt_pk_fp8_f32 v115, v90, v94
	v_cvt_pk_fp8_f32 v110, v81, v85 op_sel:[0,0,1]
	v_pk_mul_f32 v[50:51], v[50:51], s[98:99] op_sel_hi:[1,0]
	v_pk_mul_f32 v[54:55], v[54:55], s[98:99] op_sel_hi:[1,0]
	v_cvt_pk_fp8_f32 v112, v50, v54 op_sel:[0,0,1]
	v_pk_mul_f32 v[86:87], v[86:87], s[98:99] op_sel_hi:[1,0]
	v_pk_mul_f32 v[98:99], v[98:99], s[98:99] op_sel_hi:[1,0]
	v_pk_mul_f32 v[102:103], v[102:103], s[98:99] op_sel_hi:[1,0]
	v_cvt_pk_fp8_f32 v114, v82, v86 op_sel:[0,0,1]
	v_cvt_pk_fp8_f32 v115, v98, v102 op_sel:[0,0,1]
	v_mov_b32_e32 v40, v11
	v_cvt_pk_fp8_f32 v40, v43, v47
	v_mov_b32_e32 v41, v11
	v_cvt_pk_fp8_f32 v41, v59, v63
	v_cvt_pk_fp8_f32 v40, v51, v55 op_sel:[0,0,1]
	v_cvt_pk_fp8_f32 v41, v67, v71 op_sel:[0,0,1]
	v_mov_b32_e32 v42, v11
	v_cvt_pk_fp8_f32 v42, v75, v79
	v_mov_b32_e32 v43, v11
	v_cvt_pk_fp8_f32 v43, v91, v95
	v_cvt_pk_fp8_f32 v42, v83, v87 op_sel:[0,0,1]
	v_cvt_pk_fp8_f32 v43, v99, v103 op_sel:[0,0,1]
	global_store_dwordx4 v[226:227], v[104:107], off
	global_store_dwordx4 v[226:227], v[108:111], off offset:16
	global_store_dwordx4 v[226:227], v[112:115], off offset:32
	global_store_dwordx4 v[226:227], v[40:43], off offset:48
	s_mov_b32 s99, 0
	s_waitcnt vmcnt(4)
	s_andn2_b32 s12, 1, s64
	s_mulk_i32 s12, 0x4600
	s_add_i32 s12, s12, 0
	v_add_u32_e32 v10, s12, v33
	v_add3_u32 v22, s12, v31, v32
	v_add3_u32 v10, v10, v34, s34
	ds_write_b128 v22, v[0:3]
	ds_write2_b64 v10, v[4:5], v[6:7] offset1:1
	s_branch .LBB0_2376

.Lp13_i3_2384:
	s_lshl_b64 s[24:25], s[24:25], 2
	s_waitcnt lgkmcnt(0)
	s_add_u32 s12, s22, s24
	s_addc_u32 s23, s23, s25
	s_bfe_u32 s24, s3, 0x70003
	s_lshl_b32 s22, s24, 17
	s_add_u32 s22, s12, s22
	s_addc_u32 s23, s23, 0
	v_lshlrev_b32_e32 v192, 2, v192
	v_lshl_add_u64 v[232:233], s[22:23], 0, v[192:193]
	global_load_dwordx4 v[116:119], v192, s[22:23] nt
	s_nop 0
	v_mov_b32_e32 v180, v11
	v_mov_b32_e32 v181, v11
	v_mov_b32_e32 v182, v11
	v_mov_b32_e32 v183, v11
	v_mov_b32_e32 v184, v11
	v_mov_b32_e32 v185, v11
	v_mov_b32_e32 v186, v11
	v_mov_b32_e32 v187, v11
	v_mov_b32_e32 v188, v11
	v_mov_b32_e32 v189, v11
	v_mov_b32_e32 v190, v11
	v_mov_b32_e32 v191, v11
	s_mul_i32 s12, s20, s24
	v_ashrrev_i32_e32 v229, 31, v228
	v_lshl_add_u64 v[228:229], s[12:13], 0, v[228:229]
	v_lshl_add_u64 v[228:229], v[228:229], 4, s[18:19]
	s_mov_b32 s100, s21
	s_addk_i32 s3, 0x400
	s_waitcnt vmcnt(22)
	v_add_co_u32_e32 v120, vcc, s35, v232
	v_addc_co_u32_e32 v121, vcc, 0, v233, vcc
	global_load_dwordx4 v[120:123], v[120:121], off nt
	s_nop 0
	v_pk_mul_f32 v[40:41], v[40:41], s[98:99] op_sel_hi:[1,0]
	s_waitcnt vmcnt(22)
	v_add_co_u32_e32 v124, vcc, s36, v232
	v_addc_co_u32_e32 v125, vcc, 0, v233, vcc
	global_load_dwordx4 v[124:127], v[124:125], off nt
	s_nop 0
	v_pk_mul_f32 v[44:45], v[44:45], s[98:99] op_sel_hi:[1,0]
	v_cvt_pk_fp8_f32 v104, v40, v44
	s_waitcnt vmcnt(22)
	v_add_co_u32_e32 v128, vcc, s37, v232
	v_addc_co_u32_e32 v129, vcc, 0, v233, vcc
	global_load_dwordx4 v[128:131], v[128:129], off nt
	s_nop 0
	v_pk_mul_f32 v[48:49], v[48:49], s[98:99] op_sel_hi:[1,0]
	s_waitcnt vmcnt(22)
	v_add_co_u32_e32 v132, vcc, s38, v232
	v_addc_co_u32_e32 v133, vcc, 0, v233, vcc
	global_load_dwordx4 v[132:135], v[132:133], off nt
	s_nop 0
	v_pk_mul_f32 v[52:53], v[52:53], s[98:99] op_sel_hi:[1,0]
	s_waitcnt vmcnt(22)
	v_add_co_u32_e32 v136, vcc, s39, v232
	v_addc_co_u32_e32 v137, vcc, 0, v233, vcc
	global_load_dwordx4 v[136:139], v[136:137], off nt
	s_nop 0
	v_pk_mul_f32 v[56:57], v[56:57], s[98:99] op_sel_hi:[1,0]
	v_cvt_pk_fp8_f32 v104, v48, v52 op_sel:[0,0,1]
	s_waitcnt vmcnt(22)
	v_add_co_u32_e32 v140, vcc, s40, v232
	v_addc_co_u32_e32 v141, vcc, 0, v233, vcc
	global_load_dwordx4 v[140:143], v[140:141], off nt
	s_nop 0
	v_pk_mul_f32 v[60:61], v[60:61], s[98:99] op_sel_hi:[1,0]
	v_cvt_pk_fp8_f32 v105, v56, v60
	s_waitcnt vmcnt(22)
	v_add_co_u32_e32 v144, vcc, s41, v232
	v_addc_co_u32_e32 v145, vcc, 0, v233, vcc
	global_load_dwordx4 v[144:147], v[144:145], off nt
	s_nop 0
	v_pk_mul_f32 v[64:65], v[64:65], s[98:99] op_sel_hi:[1,0]
	s_waitcnt vmcnt(22)
	v_add_co_u32_e32 v148, vcc, s42, v232
	v_addc_co_u32_e32 v149, vcc, 0, v233, vcc
	global_load_dwordx4 v[148:151], v[148:149], off nt
	s_nop 0
	v_pk_mul_f32 v[68:69], v[68:69], s[98:99] op_sel_hi:[1,0]
	v_cvt_pk_fp8_f32 v105, v64, v68 op_sel:[0,0,1]
	s_waitcnt vmcnt(22)
	v_add_co_u32_e32 v152, vcc, s43, v232
	v_addc_co_u32_e32 v153, vcc, 0, v233, vcc
	global_load_dwordx4 v[152:155], v[152:153], off nt
	s_nop 0
	v_pk_mul_f32 v[72:73], v[72:73], s[98:99] op_sel_hi:[1,0]
	s_waitcnt vmcnt(22)
	v_add_co_u32_e32 v156, vcc, s44, v232
	v_addc_co_u32_e32 v157, vcc, 0, v233, vcc
	global_load_dwordx4 v[156:159], v[156:157], off nt
	s_nop 0
	v_pk_mul_f32 v[76:77], v[76:77], s[98:99] op_sel_hi:[1,0]
	v_cvt_pk_fp8_f32 v106, v72, v76
	s_waitcnt vmcnt(22)
	v_add_co_u32_e32 v160, vcc, s45, v232
	v_addc_co_u32_e32 v161, vcc, 0, v233, vcc
	global_load_dwordx4 v[160:163], v[160:161], off nt
	s_nop 0
	v_pk_mul_f32 v[80:81], v[80:81], s[98:99] op_sel_hi:[1,0]
	s_waitcnt vmcnt(22)
	v_add_co_u32_e32 v164, vcc, s46, v232
	v_addc_co_u32_e32 v165, vcc, 0, v233, vcc
	global_load_dwordx4 v[164:167], v[164:165], off nt
	s_nop 0
	v_pk_mul_f32 v[84:85], v[84:85], s[98:99] op_sel_hi:[1,0]
	s_waitcnt vmcnt(22)
	v_add_co_u32_e32 v168, vcc, s47, v232
	v_addc_co_u32_e32 v169, vcc, 0, v233, vcc
	global_load_dwordx4 v[168:171], v[168:169], off nt
	s_nop 0
	v_pk_mul_f32 v[88:89], v[88:89], s[98:99] op_sel_hi:[1,0]
	v_cvt_pk_fp8_f32 v106, v80, v84 op_sel:[0,0,1]
	v_pk_mul_f32 v[82:83], v[82:83], s[98:99] op_sel_hi:[1,0]
	s_waitcnt vmcnt(22)
	v_add_co_u32_e32 v172, vcc, s48, v232
	v_addc_co_u32_e32 v173, vcc, 0, v233, vcc
	global_load_dwordx4 v[172:175], v[172:173], off nt
	s_nop 0
	v_pk_mul_f32 v[92:93], v[92:93], s[98:99] op_sel_hi:[1,0]
	v_cvt_pk_fp8_f32 v107, v88, v92
	s_waitcnt vmcnt(22)
	v_add_co_u32_e32 v176, vcc, s49, v232
	v_addc_co_u32_e32 v177, vcc, 0, v233, vcc
	global_load_dwordx4 v[176:179], v[176:177], off nt
	s_nop 0
	v_pk_mul_f32 v[96:97], v[96:97], s[98:99] op_sel_hi:[1,0]
	s_waitcnt vmcnt(22)
	v_pk_mul_f32 v[100:101], v[100:101], s[98:99] op_sel_hi:[1,0]
	v_cvt_pk_fp8_f32 v107, v96, v100 op_sel:[0,0,1]
	v_cvt_pk_fp8_f32 v108, v41, v45
	v_cvt_pk_fp8_f32 v109, v57, v61
	v_cvt_pk_fp8_f32 v109, v65, v69 op_sel:[0,0,1]
	v_cvt_pk_fp8_f32 v110, v73, v77
	v_cvt_pk_fp8_f32 v111, v89, v93
	v_cvt_pk_fp8_f32 v108, v49, v53 op_sel:[0,0,1]
	v_cvt_pk_fp8_f32 v111, v97, v101 op_sel:[0,0,1]
	v_pk_mul_f32 v[42:43], v[42:43], s[98:99] op_sel_hi:[1,0]
	v_pk_mul_f32 v[46:47], v[46:47], s[98:99] op_sel_hi:[1,0]
	v_cvt_pk_fp8_f32 v112, v42, v46
	v_pk_mul_f32 v[58:59], v[58:59], s[98:99] op_sel_hi:[1,0]
	v_pk_mul_f32 v[62:63], v[62:63], s[98:99] op_sel_hi:[1,0]
	v_cvt_pk_fp8_f32 v113, v58, v62
	v_pk_mul_f32 v[66:67], v[66:67], s[98:99] op_sel_hi:[1,0]
	v_pk_mul_f32 v[70:71], v[70:71], s[98:99] op_sel_hi:[1,0]
	v_cvt_pk_fp8_f32 v113, v66, v70 op_sel:[0,0,1]
	v_pk_mul_f32 v[74:75], v[74:75], s[98:99] op_sel_hi:[1,0]
	v_pk_mul_f32 v[78:79], v[78:79], s[98:99] op_sel_hi:[1,0]
	v_cvt_pk_fp8_f32 v114, v74, v78
	v_pk_mul_f32 v[90:91], v[90:91], s[98:99] op_sel_hi:[1,0]
	v_pk_mul_f32 v[94:95], v[94:95], s[98:99] op_sel_hi:[1,0]
	v_cvt_pk_fp8_f32 v115, v90, v94
	v_cvt_pk_fp8_f32 v110, v81, v85 op_sel:[0,0,1]
	v_pk_mul_f32 v[50:51], v[50:51], s[98:99] op_sel_hi:[1,0]
	v_pk_mul_f32 v[54:55], v[54:55], s[98:99] op_sel_hi:[1,0]
	v_cvt_pk_fp8_f32 v112, v50, v54 op_sel:[0,0,1]
	v_pk_mul_f32 v[86:87], v[86:87], s[98:99] op_sel_hi:[1,0]
	v_pk_mul_f32 v[98:99], v[98:99], s[98:99] op_sel_hi:[1,0]
	v_pk_mul_f32 v[102:103], v[102:103], s[98:99] op_sel_hi:[1,0]
	v_cvt_pk_fp8_f32 v114, v82, v86 op_sel:[0,0,1]
	v_cvt_pk_fp8_f32 v115, v98, v102 op_sel:[0,0,1]
	v_mov_b32_e32 v40, v11
	v_cvt_pk_fp8_f32 v40, v43, v47
	v_mov_b32_e32 v41, v11
	v_cvt_pk_fp8_f32 v41, v59, v63
	v_cvt_pk_fp8_f32 v40, v51, v55 op_sel:[0,0,1]
	v_cvt_pk_fp8_f32 v41, v67, v71 op_sel:[0,0,1]
	v_mov_b32_e32 v42, v11
	v_cvt_pk_fp8_f32 v42, v75, v79
	v_mov_b32_e32 v43, v11
	v_cvt_pk_fp8_f32 v43, v91, v95
	v_cvt_pk_fp8_f32 v42, v83, v87 op_sel:[0,0,1]
	v_cvt_pk_fp8_f32 v43, v99, v103 op_sel:[0,0,1]
	global_store_dwordx4 v[226:227], v[104:107], off
	global_store_dwordx4 v[226:227], v[108:111], off offset:16
	global_store_dwordx4 v[226:227], v[112:115], off offset:32
	global_store_dwordx4 v[226:227], v[40:43], off offset:48
	s_mov_b32 s99, 4
	s_waitcnt vmcnt(20)
	s_andn2_b32 s12, 1, s64
	s_mulk_i32 s12, 0x4600
	s_add_i32 s12, s12, 0
	v_add_u32_e32 v10, s12, v33
	v_add3_u32 v22, s12, v31, v32
	v_add3_u32 v10, v10, v34, s34
	ds_write_b128 v22, v[0:3]
	ds_write2_b64 v10, v[4:5], v[6:7] offset1:1
	s_branch .LBB0_2376
.Lp13_st3c:
	s_waitcnt vmcnt(21)
	v_pk_mul_f32 v[40:41], v[40:41], s[98:99] op_sel_hi:[1,0]
	s_waitcnt vmcnt(20)
	v_pk_mul_f32 v[44:45], v[44:45], s[98:99] op_sel_hi:[1,0]
	v_cvt_pk_fp8_f32 v104, v40, v44
	s_waitcnt vmcnt(19)
	v_pk_mul_f32 v[48:49], v[48:49], s[98:99] op_sel_hi:[1,0]
	s_waitcnt vmcnt(18)
	v_pk_mul_f32 v[52:53], v[52:53], s[98:99] op_sel_hi:[1,0]
	s_waitcnt vmcnt(17)
	v_pk_mul_f32 v[56:57], v[56:57], s[98:99] op_sel_hi:[1,0]
	v_cvt_pk_fp8_f32 v104, v48, v52 op_sel:[0,0,1]
	s_waitcnt vmcnt(16)
	v_pk_mul_f32 v[60:61], v[60:61], s[98:99] op_sel_hi:[1,0]
	v_cvt_pk_fp8_f32 v105, v56, v60
	s_waitcnt vmcnt(15)
	v_pk_mul_f32 v[64:65], v[64:65], s[98:99] op_sel_hi:[1,0]
	s_waitcnt vmcnt(14)
	v_pk_mul_f32 v[68:69], v[68:69], s[98:99] op_sel_hi:[1,0]
	v_cvt_pk_fp8_f32 v105, v64, v68 op_sel:[0,0,1]
	s_waitcnt vmcnt(13)
	v_pk_mul_f32 v[72:73], v[72:73], s[98:99] op_sel_hi:[1,0]
	s_waitcnt vmcnt(12)
	v_pk_mul_f32 v[76:77], v[76:77], s[98:99] op_sel_hi:[1,0]
	v_cvt_pk_fp8_f32 v106, v72, v76
	s_waitcnt vmcnt(11)
	v_pk_mul_f32 v[80:81], v[80:81], s[98:99] op_sel_hi:[1,0]
	s_waitcnt vmcnt(10)
	v_pk_mul_f32 v[84:85], v[84:85], s[98:99] op_sel_hi:[1,0]
	s_waitcnt vmcnt(9)
	v_pk_mul_f32 v[88:89], v[88:89], s[98:99] op_sel_hi:[1,0]
	v_cvt_pk_fp8_f32 v106, v80, v84 op_sel:[0,0,1]
	v_pk_mul_f32 v[82:83], v[82:83], s[98:99] op_sel_hi:[1,0]
	s_waitcnt vmcnt(8)
	v_pk_mul_f32 v[92:93], v[92:93], s[98:99] op_sel_hi:[1,0]
	v_cvt_pk_fp8_f32 v107, v88, v92
	s_waitcnt vmcnt(7)
	v_pk_mul_f32 v[96:97], v[96:97], s[98:99] op_sel_hi:[1,0]
	s_waitcnt vmcnt(6)
	v_pk_mul_f32 v[100:101], v[100:101], s[98:99] op_sel_hi:[1,0]
	v_cvt_pk_fp8_f32 v107, v96, v100 op_sel:[0,0,1]
	v_cvt_pk_fp8_f32 v108, v41, v45
	v_cvt_pk_fp8_f32 v109, v57, v61
	v_cvt_pk_fp8_f32 v109, v65, v69 op_sel:[0,0,1]
	v_cvt_pk_fp8_f32 v110, v73, v77
	v_cvt_pk_fp8_f32 v111, v89, v93
	v_cvt_pk_fp8_f32 v108, v49, v53 op_sel:[0,0,1]
	v_cvt_pk_fp8_f32 v111, v97, v101 op_sel:[0,0,1]
	v_pk_mul_f32 v[42:43], v[42:43], s[98:99] op_sel_hi:[1,0]
	v_pk_mul_f32 v[46:47], v[46:47], s[98:99] op_sel_hi:[1,0]
	v_cvt_pk_fp8_f32 v112, v42, v46
	v_pk_mul_f32 v[58:59], v[58:59], s[98:99] op_sel_hi:[1,0]
	v_pk_mul_f32 v[62:63], v[62:63], s[98:99] op_sel_hi:[1,0]
	v_cvt_pk_fp8_f32 v113, v58, v62
	v_pk_mul_f32 v[66:67], v[66:67], s[98:99] op_sel_hi:[1,0]
	v_pk_mul_f32 v[70:71], v[70:71], s[98:99] op_sel_hi:[1,0]
	v_cvt_pk_fp8_f32 v113, v66, v70 op_sel:[0,0,1]
	v_pk_mul_f32 v[74:75], v[74:75], s[98:99] op_sel_hi:[1,0]
	v_pk_mul_f32 v[78:79], v[78:79], s[98:99] op_sel_hi:[1,0]
	v_cvt_pk_fp8_f32 v114, v74, v78
	v_pk_mul_f32 v[90:91], v[90:91], s[98:99] op_sel_hi:[1,0]
	v_pk_mul_f32 v[94:95], v[94:95], s[98:99] op_sel_hi:[1,0]
	v_cvt_pk_fp8_f32 v115, v90, v94
	v_cvt_pk_fp8_f32 v110, v81, v85 op_sel:[0,0,1]
	v_pk_mul_f32 v[50:51], v[50:51], s[98:99] op_sel_hi:[1,0]
	v_pk_mul_f32 v[54:55], v[54:55], s[98:99] op_sel_hi:[1,0]
	v_cvt_pk_fp8_f32 v112, v50, v54 op_sel:[0,0,1]
	v_pk_mul_f32 v[86:87], v[86:87], s[98:99] op_sel_hi:[1,0]
	v_pk_mul_f32 v[98:99], v[98:99], s[98:99] op_sel_hi:[1,0]
	v_pk_mul_f32 v[102:103], v[102:103], s[98:99] op_sel_hi:[1,0]
	v_cvt_pk_fp8_f32 v114, v82, v86 op_sel:[0,0,1]
	v_cvt_pk_fp8_f32 v115, v98, v102 op_sel:[0,0,1]
	v_mov_b32_e32 v40, v11
	v_cvt_pk_fp8_f32 v40, v43, v47
	v_mov_b32_e32 v41, v11
	v_cvt_pk_fp8_f32 v41, v59, v63
	v_cvt_pk_fp8_f32 v40, v51, v55 op_sel:[0,0,1]
	v_cvt_pk_fp8_f32 v41, v67, v71 op_sel:[0,0,1]
	v_mov_b32_e32 v42, v11
	v_cvt_pk_fp8_f32 v42, v75, v79
	v_mov_b32_e32 v43, v11
	v_cvt_pk_fp8_f32 v43, v91, v95
	v_cvt_pk_fp8_f32 v42, v83, v87 op_sel:[0,0,1]
	v_cvt_pk_fp8_f32 v43, v99, v103 op_sel:[0,0,1]
	global_store_dwordx4 v[226:227], v[104:107], off
	global_store_dwordx4 v[226:227], v[108:111], off offset:16
	global_store_dwordx4 v[226:227], v[112:115], off offset:32
	global_store_dwordx4 v[226:227], v[40:43], off offset:48
	s_mov_b32 s99, 0
	s_waitcnt vmcnt(4)
	s_andn2_b32 s12, 1, s64
	s_mulk_i32 s12, 0x4600
	s_add_i32 s12, s12, 0
	v_add_u32_e32 v10, s12, v33
	v_add3_u32 v22, s12, v31, v32
	v_add3_u32 v10, v10, v34, s34
	ds_write_b128 v22, v[0:3]
	ds_write2_b64 v10, v[4:5], v[6:7] offset1:1
	s_branch .LBB0_2376

.Lp13_i4_2384:
	s_lshl_b64 s[24:25], s[24:25], 2
	s_waitcnt lgkmcnt(0)
	s_add_u32 s12, s22, s24
	s_addc_u32 s23, s23, s25
	s_bfe_u32 s24, s3, 0x70003
	s_lshl_b32 s22, s24, 17
	s_add_u32 s22, s12, s22
	s_addc_u32 s23, s23, 0
	v_lshlrev_b32_e32 v10, 2, v10
	v_lshl_add_u64 v[230:231], s[22:23], 0, v[10:11]
	global_load_dwordx4 v[40:43], v10, s[22:23] nt
	s_nop 0
	v_mov_b32_e32 v104, v11
	v_mov_b32_e32 v105, v11
	v_mov_b32_e32 v106, v11
	v_mov_b32_e32 v107, v11
	v_mov_b32_e32 v108, v11
	v_mov_b32_e32 v109, v11
	v_mov_b32_e32 v110, v11
	v_mov_b32_e32 v111, v11
	v_mov_b32_e32 v112, v11
	v_mov_b32_e32 v113, v11
	v_mov_b32_e32 v114, v11
	v_mov_b32_e32 v115, v11
	s_mul_i32 s12, s20, s24
	v_ashrrev_i32_e32 v227, 31, v226
	v_lshl_add_u64 v[226:227], s[12:13], 0, v[226:227]
	v_lshl_add_u64 v[226:227], v[226:227], 4, s[18:19]
	s_mov_b32 s98, s21
	s_addk_i32 s3, 0x400
	s_waitcnt vmcnt(22)
	v_add_co_u32_e32 v44, vcc, s35, v230
	v_addc_co_u32_e32 v45, vcc, 0, v231, vcc
	global_load_dwordx4 v[44:47], v[44:45], off nt
	s_nop 0
	v_pk_mul_f32 v[116:117], v[116:117], s[100:101] op_sel_hi:[1,0]
	s_waitcnt vmcnt(22)
	v_add_co_u32_e32 v48, vcc, s36, v230
	v_addc_co_u32_e32 v49, vcc, 0, v231, vcc
	global_load_dwordx4 v[48:51], v[48:49], off nt
	s_nop 0
	v_pk_mul_f32 v[120:121], v[120:121], s[100:101] op_sel_hi:[1,0]
	v_cvt_pk_fp8_f32 v180, v116, v120
	s_waitcnt vmcnt(22)
	v_add_co_u32_e32 v52, vcc, s37, v230
	v_addc_co_u32_e32 v53, vcc, 0, v231, vcc
	global_load_dwordx4 v[52:55], v[52:53], off nt
	s_nop 0
	v_pk_mul_f32 v[124:125], v[124:125], s[100:101] op_sel_hi:[1,0]
	s_waitcnt vmcnt(22)
	v_add_co_u32_e32 v56, vcc, s38, v230
	v_addc_co_u32_e32 v57, vcc, 0, v231, vcc
	global_load_dwordx4 v[56:59], v[56:57], off nt
	s_nop 0
	v_pk_mul_f32 v[128:129], v[128:129], s[100:101] op_sel_hi:[1,0]
	s_waitcnt vmcnt(22)
	v_add_co_u32_e32 v60, vcc, s39, v230
	v_addc_co_u32_e32 v61, vcc, 0, v231, vcc
	global_load_dwordx4 v[60:63], v[60:61], off nt
	s_nop 0
	v_pk_mul_f32 v[132:133], v[132:133], s[100:101] op_sel_hi:[1,0]
	v_cvt_pk_fp8_f32 v180, v124, v128 op_sel:[0,0,1]
	s_waitcnt vmcnt(22)
	v_add_co_u32_e32 v64, vcc, s40, v230
	v_addc_co_u32_e32 v65, vcc, 0, v231, vcc
	global_load_dwordx4 v[64:67], v[64:65], off nt
	s_nop 0
	v_pk_mul_f32 v[136:137], v[136:137], s[100:101] op_sel_hi:[1,0]
	v_cvt_pk_fp8_f32 v181, v132, v136
	s_waitcnt vmcnt(22)
	v_add_co_u32_e32 v68, vcc, s41, v230
	v_addc_co_u32_e32 v69, vcc, 0, v231, vcc
	global_load_dwordx4 v[68:71], v[68:69], off nt
	s_nop 0
	v_pk_mul_f32 v[140:141], v[140:141], s[100:101] op_sel_hi:[1,0]
	s_waitcnt vmcnt(22)
	v_add_co_u32_e32 v72, vcc, s42, v230
	v_addc_co_u32_e32 v73, vcc, 0, v231, vcc
	global_load_dwordx4 v[72:75], v[72:73], off nt
	s_nop 0
	v_pk_mul_f32 v[144:145], v[144:145], s[100:101] op_sel_hi:[1,0]
	v_cvt_pk_fp8_f32 v181, v140, v144 op_sel:[0,0,1]
	s_waitcnt vmcnt(22)
	v_add_co_u32_e32 v76, vcc, s43, v230
	v_addc_co_u32_e32 v77, vcc, 0, v231, vcc
	global_load_dwordx4 v[76:79], v[76:77], off nt
	s_nop 0
	v_pk_mul_f32 v[148:149], v[148:149], s[100:101] op_sel_hi:[1,0]
	s_waitcnt vmcnt(22)
	v_add_co_u32_e32 v80, vcc, s44, v230
	v_addc_co_u32_e32 v81, vcc, 0, v231, vcc
	global_load_dwordx4 v[80:83], v[80:81], off nt
	s_nop 0
	v_pk_mul_f32 v[152:153], v[152:153], s[100:101] op_sel_hi:[1,0]
	v_cvt_pk_fp8_f32 v182, v148, v152
	s_waitcnt vmcnt(22)
	v_add_co_u32_e32 v84, vcc, s45, v230
	v_addc_co_u32_e32 v85, vcc, 0, v231, vcc
	global_load_dwordx4 v[84:87], v[84:85], off nt
	s_nop 0
	v_pk_mul_f32 v[156:157], v[156:157], s[100:101] op_sel_hi:[1,0]
	s_waitcnt vmcnt(22)
	v_add_co_u32_e32 v88, vcc, s46, v230
	v_addc_co_u32_e32 v89, vcc, 0, v231, vcc
	global_load_dwordx4 v[88:91], v[88:89], off nt
	s_nop 0
	v_pk_mul_f32 v[160:161], v[160:161], s[100:101] op_sel_hi:[1,0]
	s_waitcnt vmcnt(22)
	v_add_co_u32_e32 v92, vcc, s47, v230
	v_addc_co_u32_e32 v93, vcc, 0, v231, vcc
	global_load_dwordx4 v[92:95], v[92:93], off nt
	s_nop 0
	v_pk_mul_f32 v[164:165], v[164:165], s[100:101] op_sel_hi:[1,0]
	v_cvt_pk_fp8_f32 v182, v156, v160 op_sel:[0,0,1]
	v_pk_mul_f32 v[158:159], v[158:159], s[100:101] op_sel_hi:[1,0]
	s_waitcnt vmcnt(22)
	v_add_co_u32_e32 v96, vcc, s48, v230
	v_addc_co_u32_e32 v97, vcc, 0, v231, vcc
	global_load_dwordx4 v[96:99], v[96:97], off nt
	s_nop 0
	v_pk_mul_f32 v[168:169], v[168:169], s[100:101] op_sel_hi:[1,0]
	v_cvt_pk_fp8_f32 v183, v164, v168
	s_waitcnt vmcnt(22)
	v_add_co_u32_e32 v100, vcc, s49, v230
	v_addc_co_u32_e32 v101, vcc, 0, v231, vcc
	global_load_dwordx4 v[100:103], v[100:101], off nt
	s_nop 0
	v_pk_mul_f32 v[172:173], v[172:173], s[100:101] op_sel_hi:[1,0]
	s_waitcnt vmcnt(22)
	v_pk_mul_f32 v[176:177], v[176:177], s[100:101] op_sel_hi:[1,0]
	v_cvt_pk_fp8_f32 v183, v172, v176 op_sel:[0,0,1]
	v_cvt_pk_fp8_f32 v184, v117, v121
	v_cvt_pk_fp8_f32 v185, v133, v137
	v_cvt_pk_fp8_f32 v185, v141, v145 op_sel:[0,0,1]
	v_cvt_pk_fp8_f32 v186, v149, v153
	v_cvt_pk_fp8_f32 v187, v165, v169
	v_cvt_pk_fp8_f32 v184, v125, v129 op_sel:[0,0,1]
	v_cvt_pk_fp8_f32 v187, v173, v177 op_sel:[0,0,1]
	v_pk_mul_f32 v[118:119], v[118:119], s[100:101] op_sel_hi:[1,0]
	v_pk_mul_f32 v[122:123], v[122:123], s[100:101] op_sel_hi:[1,0]
	v_cvt_pk_fp8_f32 v188, v118, v122
	v_pk_mul_f32 v[134:135], v[134:135], s[100:101] op_sel_hi:[1,0]
	v_pk_mul_f32 v[138:139], v[138:139], s[100:101] op_sel_hi:[1,0]
	v_cvt_pk_fp8_f32 v189, v134, v138
	v_pk_mul_f32 v[142:143], v[142:143], s[100:101] op_sel_hi:[1,0]
	v_pk_mul_f32 v[146:147], v[146:147], s[100:101] op_sel_hi:[1,0]
	v_cvt_pk_fp8_f32 v189, v142, v146 op_sel:[0,0,1]
	v_pk_mul_f32 v[150:151], v[150:151], s[100:101] op_sel_hi:[1,0]
	v_pk_mul_f32 v[154:155], v[154:155], s[100:101] op_sel_hi:[1,0]
	v_cvt_pk_fp8_f32 v190, v150, v154
	v_pk_mul_f32 v[166:167], v[166:167], s[100:101] op_sel_hi:[1,0]
	v_pk_mul_f32 v[170:171], v[170:171], s[100:101] op_sel_hi:[1,0]
	v_cvt_pk_fp8_f32 v191, v166, v170
	v_cvt_pk_fp8_f32 v186, v157, v161 op_sel:[0,0,1]
	v_pk_mul_f32 v[126:127], v[126:127], s[100:101] op_sel_hi:[1,0]
	v_pk_mul_f32 v[130:131], v[130:131], s[100:101] op_sel_hi:[1,0]
	v_cvt_pk_fp8_f32 v188, v126, v130 op_sel:[0,0,1]
	v_pk_mul_f32 v[162:163], v[162:163], s[100:101] op_sel_hi:[1,0]
	v_pk_mul_f32 v[174:175], v[174:175], s[100:101] op_sel_hi:[1,0]
	v_pk_mul_f32 v[178:179], v[178:179], s[100:101] op_sel_hi:[1,0]
	v_cvt_pk_fp8_f32 v190, v158, v162 op_sel:[0,0,1]
	v_cvt_pk_fp8_f32 v191, v174, v178 op_sel:[0,0,1]
	v_mov_b32_e32 v116, v11
	v_cvt_pk_fp8_f32 v116, v119, v123
	v_mov_b32_e32 v117, v11
	v_cvt_pk_fp8_f32 v117, v135, v139
	v_cvt_pk_fp8_f32 v116, v127, v131 op_sel:[0,0,1]
	v_cvt_pk_fp8_f32 v117, v143, v147 op_sel:[0,0,1]
	v_mov_b32_e32 v118, v11
	v_cvt_pk_fp8_f32 v118, v151, v155
	v_mov_b32_e32 v119, v11
	v_cvt_pk_fp8_f32 v119, v167, v171
	v_cvt_pk_fp8_f32 v118, v159, v163 op_sel:[0,0,1]
	v_cvt_pk_fp8_f32 v119, v175, v179 op_sel:[0,0,1]
	global_store_dwordx4 v[228:229], v[180:183], off
	global_store_dwordx4 v[228:229], v[184:187], off offset:16
	global_store_dwordx4 v[228:229], v[188:191], off offset:32
	global_store_dwordx4 v[228:229], v[116:119], off offset:48
	s_mov_b32 s99, 3
	s_waitcnt vmcnt(20)
	s_andn2_b32 s12, 1, s64
	s_mulk_i32 s12, 0x4600
	s_add_i32 s12, s12, 0
	v_add_u32_e32 v10, s12, v33
	v_add3_u32 v22, s12, v31, v32
	v_add3_u32 v10, v10, v34, s34
	ds_write_b128 v22, v[0:3]
	ds_write2_b64 v10, v[4:5], v[6:7] offset1:1
	s_branch .LBB0_2376
.Lp13_st4c:
	s_waitcnt vmcnt(21)
	v_pk_mul_f32 v[116:117], v[116:117], s[100:101] op_sel_hi:[1,0]
	s_waitcnt vmcnt(20)
	v_pk_mul_f32 v[120:121], v[120:121], s[100:101] op_sel_hi:[1,0]
	v_cvt_pk_fp8_f32 v180, v116, v120
	s_waitcnt vmcnt(19)
	v_pk_mul_f32 v[124:125], v[124:125], s[100:101] op_sel_hi:[1,0]
	s_waitcnt vmcnt(18)
	v_pk_mul_f32 v[128:129], v[128:129], s[100:101] op_sel_hi:[1,0]
	s_waitcnt vmcnt(17)
	v_pk_mul_f32 v[132:133], v[132:133], s[100:101] op_sel_hi:[1,0]
	v_cvt_pk_fp8_f32 v180, v124, v128 op_sel:[0,0,1]
	s_waitcnt vmcnt(16)
	v_pk_mul_f32 v[136:137], v[136:137], s[100:101] op_sel_hi:[1,0]
	v_cvt_pk_fp8_f32 v181, v132, v136
	s_waitcnt vmcnt(15)
	v_pk_mul_f32 v[140:141], v[140:141], s[100:101] op_sel_hi:[1,0]
	s_waitcnt vmcnt(14)
	v_pk_mul_f32 v[144:145], v[144:145], s[100:101] op_sel_hi:[1,0]
	v_cvt_pk_fp8_f32 v181, v140, v144 op_sel:[0,0,1]
	s_waitcnt vmcnt(13)
	v_pk_mul_f32 v[148:149], v[148:149], s[100:101] op_sel_hi:[1,0]
	s_waitcnt vmcnt(12)
	v_pk_mul_f32 v[152:153], v[152:153], s[100:101] op_sel_hi:[1,0]
	v_cvt_pk_fp8_f32 v182, v148, v152
	s_waitcnt vmcnt(11)
	v_pk_mul_f32 v[156:157], v[156:157], s[100:101] op_sel_hi:[1,0]
	s_waitcnt vmcnt(10)
	v_pk_mul_f32 v[160:161], v[160:161], s[100:101] op_sel_hi:[1,0]
	s_waitcnt vmcnt(9)
	v_pk_mul_f32 v[164:165], v[164:165], s[100:101] op_sel_hi:[1,0]
	v_cvt_pk_fp8_f32 v182, v156, v160 op_sel:[0,0,1]
	v_pk_mul_f32 v[158:159], v[158:159], s[100:101] op_sel_hi:[1,0]
	s_waitcnt vmcnt(8)
	v_pk_mul_f32 v[168:169], v[168:169], s[100:101] op_sel_hi:[1,0]
	v_cvt_pk_fp8_f32 v183, v164, v168
	s_waitcnt vmcnt(7)
	v_pk_mul_f32 v[172:173], v[172:173], s[100:101] op_sel_hi:[1,0]
	s_waitcnt vmcnt(6)
	v_pk_mul_f32 v[176:177], v[176:177], s[100:101] op_sel_hi:[1,0]
	v_cvt_pk_fp8_f32 v183, v172, v176 op_sel:[0,0,1]
	v_cvt_pk_fp8_f32 v184, v117, v121
	v_cvt_pk_fp8_f32 v185, v133, v137
	v_cvt_pk_fp8_f32 v185, v141, v145 op_sel:[0,0,1]
	v_cvt_pk_fp8_f32 v186, v149, v153
	v_cvt_pk_fp8_f32 v187, v165, v169
	v_cvt_pk_fp8_f32 v184, v125, v129 op_sel:[0,0,1]
	v_cvt_pk_fp8_f32 v187, v173, v177 op_sel:[0,0,1]
	v_pk_mul_f32 v[118:119], v[118:119], s[100:101] op_sel_hi:[1,0]
	v_pk_mul_f32 v[122:123], v[122:123], s[100:101] op_sel_hi:[1,0]
	v_cvt_pk_fp8_f32 v188, v118, v122
	v_pk_mul_f32 v[134:135], v[134:135], s[100:101] op_sel_hi:[1,0]
	v_pk_mul_f32 v[138:139], v[138:139], s[100:101] op_sel_hi:[1,0]
	v_cvt_pk_fp8_f32 v189, v134, v138
	v_pk_mul_f32 v[142:143], v[142:143], s[100:101] op_sel_hi:[1,0]
	v_pk_mul_f32 v[146:147], v[146:147], s[100:101] op_sel_hi:[1,0]
	v_cvt_pk_fp8_f32 v189, v142, v146 op_sel:[0,0,1]
	v_pk_mul_f32 v[150:151], v[150:151], s[100:101] op_sel_hi:[1,0]
	v_pk_mul_f32 v[154:155], v[154:155], s[100:101] op_sel_hi:[1,0]
	v_cvt_pk_fp8_f32 v190, v150, v154
	v_pk_mul_f32 v[166:167], v[166:167], s[100:101] op_sel_hi:[1,0]
	v_pk_mul_f32 v[170:171], v[170:171], s[100:101] op_sel_hi:[1,0]
	v_cvt_pk_fp8_f32 v191, v166, v170
	v_cvt_pk_fp8_f32 v186, v157, v161 op_sel:[0,0,1]
	v_pk_mul_f32 v[126:127], v[126:127], s[100:101] op_sel_hi:[1,0]
	v_pk_mul_f32 v[130:131], v[130:131], s[100:101] op_sel_hi:[1,0]
	v_cvt_pk_fp8_f32 v188, v126, v130 op_sel:[0,0,1]
	v_pk_mul_f32 v[162:163], v[162:163], s[100:101] op_sel_hi:[1,0]
	v_pk_mul_f32 v[174:175], v[174:175], s[100:101] op_sel_hi:[1,0]
	v_pk_mul_f32 v[178:179], v[178:179], s[100:101] op_sel_hi:[1,0]
	v_cvt_pk_fp8_f32 v190, v158, v162 op_sel:[0,0,1]
	v_cvt_pk_fp8_f32 v191, v174, v178 op_sel:[0,0,1]
	v_mov_b32_e32 v116, v11
	v_cvt_pk_fp8_f32 v116, v119, v123
	v_mov_b32_e32 v117, v11
	v_cvt_pk_fp8_f32 v117, v135, v139
	v_cvt_pk_fp8_f32 v116, v127, v131 op_sel:[0,0,1]
	v_cvt_pk_fp8_f32 v117, v143, v147 op_sel:[0,0,1]
	v_mov_b32_e32 v118, v11
	v_cvt_pk_fp8_f32 v118, v151, v155
	v_mov_b32_e32 v119, v11
	v_cvt_pk_fp8_f32 v119, v167, v171
	v_cvt_pk_fp8_f32 v118, v159, v163 op_sel:[0,0,1]
	v_cvt_pk_fp8_f32 v119, v175, v179 op_sel:[0,0,1]
	global_store_dwordx4 v[228:229], v[180:183], off
	global_store_dwordx4 v[228:229], v[184:187], off offset:16
	global_store_dwordx4 v[228:229], v[188:191], off offset:32
	global_store_dwordx4 v[228:229], v[116:119], off offset:48
	s_mov_b32 s99, 0
	s_waitcnt vmcnt(4)
	s_andn2_b32 s12, 1, s64
	s_mulk_i32 s12, 0x4600
	s_add_i32 s12, s12, 0
	v_add_u32_e32 v10, s12, v33
	v_add3_u32 v22, s12, v31, v32
	v_add3_u32 v10, v10, v34, s34
	ds_write_b128 v22, v[0:3]
	ds_write2_b64 v10, v[4:5], v[6:7] offset1:1
	s_branch .LBB0_2376
